# attention c=1 x6 loop entered from the loop's initial slot state (all 30 steady step pairs run folded)
# baseline (speedup 1.0000x reference)
.Lst1_loop:
	s_cmp_lg_u32 s48, 1
	s_cbranch_scc1 .Lst1_single
	s_and_b32 s2, s46, 0xffff
	s_cmp_lg_u32 s2, 0x0
	s_cbranch_scc1 .Lst1_single
	s_cmp_lt_u32 s47, 50
	s_cbranch_scc1 .Lst1_u6

.Lst1_u6_loop:
	s_add_i32 s49, s58, 0x4000
	s_mov_b32 m0, s49
	s_nop 0
	global_load_lds_dwordx4 v198, s[98:99]
	s_add_i32 m0, s49, 0x400
	s_nop 0
	global_load_lds_dwordx4 v194, s[98:99]
	s_add_i32 s49, s46, 0xffffc000
	s_add_i32 s49, s58, 0xc000
	s_add_i32 m0, s49, 0xc000
	s_nop 0
	global_load_lds_dwordx4 v196, s[100:101]
	s_add_i32 m0, s49, 0xc400
	s_nop 0
	global_load_lds_dwordx4 v192, s[100:101]
	ds_read_b128 v[140:143], v206 offset:49152
	ds_read_b128 v[148:151], v206 offset:53248
	ds_read_b128 v[152:155], v206 offset:57344
	ds_read_b128 v[156:159], v206 offset:61440
	s_waitcnt lgkmcnt(0)
	v_mfma_f32_32x32x16_bf16 v[80:95], v[140:143], v[144:147], v[80:95]
	ds_read_b128 v[140:143], v207 offset:49152
	v_mfma_f32_32x32x16_bf16 v[64:79], v[148:151], v[144:147], v[64:79]
	ds_read_b128 v[148:151], v207 offset:53248
	v_mfma_f32_32x32x16_bf16 v[16:31], v[152:155], v[144:147], v[16:31]
	ds_read_b128 v[152:155], v207 offset:57344
	v_mfma_f32_32x32x16_bf16 v[0:15], v[156:159], v[144:147], v[0:15]
	ds_read_b128 v[144:147], v207 offset:61440
	s_waitcnt lgkmcnt(0)
	v_mfma_f32_32x32x16_bf16 v[80:95], v[140:143], v[128:131], v[80:95]
	ds_read_b128 v[140:143], v208 offset:49152
	v_mfma_f32_32x32x16_bf16 v[64:79], v[148:151], v[128:131], v[64:79]
	ds_read_b128 v[148:151], v208 offset:53248
	v_mfma_f32_32x32x16_bf16 v[16:31], v[152:155], v[128:131], v[16:31]
	ds_read_b128 v[152:155], v208 offset:57344
	v_mfma_f32_32x32x16_bf16 v[0:15], v[144:147], v[128:131], v[0:15]
	ds_read_b128 v[128:131], v208 offset:61440
	s_waitcnt lgkmcnt(0)
	v_mfma_f32_32x32x16_bf16 v[80:95], v[140:143], v[132:135], v[80:95]
	ds_read_b128 v[140:143], v209 offset:49152
	v_mfma_f32_32x32x16_bf16 v[64:79], v[148:151], v[132:135], v[64:79]
	ds_read_b128 v[144:147], v209 offset:53248
	v_mfma_f32_32x32x16_bf16 v[16:31], v[152:155], v[132:135], v[16:31]
	ds_read_b128 v[148:151], v209 offset:57344
	v_mfma_f32_32x32x16_bf16 v[0:15], v[128:131], v[132:135], v[0:15]
	ds_read_b128 v[128:131], v209 offset:61440
	s_waitcnt lgkmcnt(0)
	v_mfma_f32_32x32x16_bf16 v[80:95], v[140:143], v[136:139], v[80:95]
	ds_read_b128 v[132:135], v205 offset:32768
	v_mfma_f32_32x32x16_bf16 v[64:79], v[144:147], v[136:139], v[64:79]
	ds_read_b128 v[140:143], v205 offset:40960
	v_mfma_f32_32x32x16_bf16 v[16:31], v[148:151], v[136:139], v[16:31]
	ds_read_b128 v[176:179], v211 offset:32768
	v_mfma_f32_32x32x16_bf16 v[0:15], v[128:131], v[136:139], v[0:15]
	ds_read_b128 v[182:185], v211 offset:40960
	s_waitcnt lgkmcnt(0)
	v_mfma_f32_32x32x16_bf16 v[144:159], v[132:135], v[160:163], 0
	ds_read_b128 v[186:189], v212 offset:32768
	v_exp_f32_e32 v220, v112
	v_exp_f32_e32 v221, v113
	v_exp_f32_e32 v222, v114
	v_exp_f32_e32 v223, v115
	v_mfma_f32_32x32x16_bf16 v[128:143], v[140:143], v[160:163], 0
	ds_read_b128 v[216:219], v212 offset:40960
	v_exp_f32_e32 v224, v116
	v_exp_f32_e32 v225, v117
	v_exp_f32_e32 v226, v118
	v_exp_f32_e32 v227, v119
	v_mfma_f32_32x32x16_bf16 v[144:159], v[176:179], v[164:167], v[144:159]
	ds_read_b128 v[116:119], v213 offset:32768
	v_exp_f32_e32 v228, v120
	v_exp_f32_e32 v229, v121
	v_exp_f32_e32 v230, v122
	v_exp_f32_e32 v231, v123
	v_cvt_pk_bf16_f32 v112, v220, v221
	v_cvt_pk_bf16_f32 v113, v222, v223
	v_cvt_pk_bf16_f32 v114, v224, v225
	v_cvt_pk_bf16_f32 v115, v226, v227
	v_pk_add_f32 v[122:123], v[226:227], v[222:223]
	v_pk_add_f32 v[120:121], v[224:225], v[220:221]
	v_mfma_f32_32x32x16_bf16 v[128:143], v[182:185], v[164:167], v[128:143]
	ds_read_b128 v[176:179], v213 offset:40960
	v_exp_f32_e32 v124, v124
	v_exp_f32_e32 v125, v125
	v_exp_f32_e32 v126, v126
	v_exp_f32_e32 v127, v127
	s_waitcnt lgkmcnt(0)
	v_mfma_f32_32x32x16_bf16 v[144:159], v[186:189], v[168:171], v[144:159]
	v_add_f32_e64 v122, v230, v122
	v_add_f32_e64 v123, v231, v123
	v_add_f32_e64 v120, v228, v120
	v_add_f32_e64 v121, v229, v121
	v_exp_f32_e32 v182, v96
	v_exp_f32_e32 v183, v97
	v_exp_f32_e32 v184, v98
	v_exp_f32_e32 v185, v99
	v_cvt_pk_bf16_f32 v96, v228, v229
	v_cvt_pk_bf16_f32 v97, v230, v231
	v_cvt_pk_bf16_f32 v98, v124, v125
	v_cvt_pk_bf16_f32 v99, v126, v127
	v_pk_add_f32 v[122:123], v[126:127], v[122:123]
	v_pk_add_f32 v[120:121], v[124:125], v[120:121]
	v_mfma_f32_32x32x16_bf16 v[128:143], v[216:219], v[168:171], v[128:143]
	v_exp_f32_e32 v124, v100
	v_exp_f32_e32 v125, v101
	v_exp_f32_e32 v126, v102
	v_exp_f32_e32 v127, v103
	v_mfma_f32_32x32x16_bf16 v[144:159], v[116:119], v[172:175], v[144:159]
	v_exp_f32_e32 v186, v104
	v_exp_f32_e32 v187, v105
	v_exp_f32_e32 v188, v106
	v_exp_f32_e32 v189, v107
	v_pk_add_f32 v[106:107], v[184:185], v[122:123]
	v_pk_add_f32 v[104:105], v[182:183], v[120:121]
	v_cvt_pk_bf16_f32 v100, v182, v183
	v_cvt_pk_bf16_f32 v101, v184, v185
	v_cvt_pk_bf16_f32 v102, v124, v125
	v_cvt_pk_bf16_f32 v103, v126, v127
	v_pk_add_f32 v[118:119], v[126:127], v[106:107]
	v_pk_add_f32 v[116:117], v[124:125], v[104:105]
	v_mfma_f32_32x32x16_bf16 v[128:143], v[176:179], v[172:175], v[128:143]
	v_exp_f32_e32 v120, v108
	v_exp_f32_e32 v121, v109
	v_exp_f32_e32 v122, v110
	v_exp_f32_e32 v123, v111
	v_pk_add_f32 v[110:111], v[188:189], v[118:119]
	v_pk_add_f32 v[108:109], v[186:187], v[116:117]
	v_cvt_pk_bf16_f32 v104, v186, v187
	v_cvt_pk_bf16_f32 v105, v188, v189
	v_cvt_pk_bf16_f32 v106, v120, v121
	v_cvt_pk_bf16_f32 v107, v122, v123
	v_pk_add_f32 v[178:179], v[122:123], v[110:111]
	v_pk_add_f32 v[176:177], v[120:121], v[108:109]
	s_waitcnt vmcnt(4) lgkmcnt(0)
	s_barrier
	s_add_u32 s70, s98, 0x18000
	s_addc_u32 s71, s99, 0
	s_add_i32 s68, 0x8000, s57
	s_mov_b32 m0, s68
	s_nop 0
	global_load_lds_dwordx4 v198, s[70:71]
	s_add_i32 m0, s68, 0x400
	s_nop 0
	global_load_lds_dwordx4 v194, s[70:71]
	s_add_u32 s2, s100, 0x80
	s_addc_u32 s3, s101, 0
	s_add_i32 s49, s58, 0
	s_add_i32 m0, s49, 0xc000
	s_nop 0
	global_load_lds_dwordx4 v196, s[2:3]
	s_add_i32 m0, s49, 0xc400
	s_nop 0
	global_load_lds_dwordx4 v192, s[2:3]
	s_add_i32 s2, s46, 0xffff4000
	ds_read_b128 v[108:111], v236
	ds_read_b128 v[116:119], v236 offset:4096
	ds_read_b128 v[120:123], v236 offset:8192
	ds_read_b128 v[124:127], v236 offset:12288
	s_waitcnt lgkmcnt(0)
	v_mfma_f32_32x32x16_bf16 v[80:95], v[108:111], v[112:115], v[80:95]
	ds_read_b128 v[108:111], v237
	v_mfma_f32_32x32x16_bf16 v[64:79], v[116:119], v[112:115], v[64:79]
	ds_read_b128 v[116:119], v237 offset:4096
	v_mfma_f32_32x32x16_bf16 v[16:31], v[120:123], v[112:115], v[16:31]
	ds_read_b128 v[120:123], v237 offset:8192
	v_mfma_f32_32x32x16_bf16 v[0:15], v[124:127], v[112:115], v[0:15]
	ds_read_b128 v[112:115], v237 offset:12288
	s_waitcnt lgkmcnt(0)
	v_mfma_f32_32x32x16_bf16 v[80:95], v[108:111], v[96:99], v[80:95]
	ds_read_b128 v[108:111], v238
	v_mfma_f32_32x32x16_bf16 v[64:79], v[116:119], v[96:99], v[64:79]
	ds_read_b128 v[116:119], v238 offset:4096
	v_mfma_f32_32x32x16_bf16 v[16:31], v[120:123], v[96:99], v[16:31]
	ds_read_b128 v[120:123], v238 offset:8192
	v_mfma_f32_32x32x16_bf16 v[0:15], v[112:115], v[96:99], v[0:15]
	ds_read_b128 v[96:99], v238 offset:12288
	s_waitcnt lgkmcnt(0)
	v_mfma_f32_32x32x16_bf16 v[80:95], v[108:111], v[100:103], v[80:95]
	ds_read_b128 v[108:111], v239
	v_mfma_f32_32x32x16_bf16 v[64:79], v[116:119], v[100:103], v[64:79]
	ds_read_b128 v[112:115], v239 offset:4096
	v_mfma_f32_32x32x16_bf16 v[16:31], v[120:123], v[100:103], v[16:31]
	ds_read_b128 v[116:119], v239 offset:8192
	v_mfma_f32_32x32x16_bf16 v[0:15], v[96:99], v[100:103], v[0:15]
	ds_read_b128 v[120:123], v239 offset:12288
	s_waitcnt lgkmcnt(0)
	v_mfma_f32_32x32x16_bf16 v[80:95], v[108:111], v[104:107], v[80:95]
	ds_read_b128 v[96:99], v205
	v_mfma_f32_32x32x16_bf16 v[64:79], v[112:115], v[104:107], v[64:79]
	ds_read_b128 v[100:103], v205 offset:8192
	v_mfma_f32_32x32x16_bf16 v[16:31], v[116:119], v[104:107], v[16:31]
	ds_read_b128 v[182:185], v211
	v_mfma_f32_32x32x16_bf16 v[0:15], v[120:123], v[104:107], v[0:15]
	ds_read_b128 v[186:189], v211 offset:8192
	s_waitcnt lgkmcnt(0)
	v_mfma_f32_32x32x16_bf16 v[112:127], v[96:99], v[160:163], 0
	ds_read_b128 v[216:219], v212
	v_exp_f32_e32 v224, v144
	v_exp_f32_e32 v225, v145
	v_exp_f32_e32 v226, v146
	v_exp_f32_e32 v227, v147
	ds_read_b128 v[220:223], v212 offset:8192
	v_mfma_f32_32x32x16_bf16 v[96:111], v[100:103], v[160:163], 0
	v_exp_f32_e32 v228, v148
	v_exp_f32_e32 v229, v149
	v_exp_f32_e32 v230, v150
	v_exp_f32_e32 v231, v151
	v_mfma_f32_32x32x16_bf16 v[112:127], v[182:185], v[164:167], v[112:127]
	ds_read_b128 v[148:151], v213
	v_exp_f32_e32 v232, v152
	v_exp_f32_e32 v233, v153
	v_exp_f32_e32 v234, v154
	v_exp_f32_e32 v235, v155
	v_cvt_pk_bf16_f32 v144, v224, v225
	v_cvt_pk_bf16_f32 v145, v226, v227
	v_cvt_pk_bf16_f32 v146, v228, v229
	v_cvt_pk_bf16_f32 v147, v230, v231
	v_pk_add_f32 v[154:155], v[230:231], v[226:227]
	v_pk_add_f32 v[152:153], v[228:229], v[224:225]
	v_mfma_f32_32x32x16_bf16 v[96:111], v[186:189], v[164:167], v[96:111]
	ds_read_b128 v[182:185], v213 offset:8192
	v_exp_f32_e32 v156, v156
	v_exp_f32_e32 v157, v157
	v_exp_f32_e32 v158, v158
	v_exp_f32_e32 v159, v159
	s_waitcnt lgkmcnt(0)
	v_mfma_f32_32x32x16_bf16 v[112:127], v[216:219], v[168:171], v[112:127]
	v_add_f32_e64 v154, v234, v154
	v_add_f32_e64 v155, v235, v155
	v_add_f32_e64 v152, v232, v152
	v_add_f32_e64 v153, v233, v153
	v_exp_f32_e32 v186, v128
	v_exp_f32_e32 v187, v129
	v_exp_f32_e32 v188, v130
	v_exp_f32_e32 v189, v131
	v_cvt_pk_bf16_f32 v128, v232, v233
	v_cvt_pk_bf16_f32 v129, v234, v235
	v_cvt_pk_bf16_f32 v130, v156, v157
	v_cvt_pk_bf16_f32 v131, v158, v159
	v_pk_add_f32 v[154:155], v[158:159], v[154:155]
	v_pk_add_f32 v[152:153], v[156:157], v[152:153]
	v_mfma_f32_32x32x16_bf16 v[96:111], v[220:223], v[168:171], v[96:111]
	v_exp_f32_e32 v156, v132
	v_exp_f32_e32 v157, v133
	v_exp_f32_e32 v158, v134
	v_exp_f32_e32 v159, v135
	v_mfma_f32_32x32x16_bf16 v[112:127], v[148:151], v[172:175], v[112:127]
	v_exp_f32_e32 v216, v136
	v_exp_f32_e32 v217, v137
	v_exp_f32_e32 v218, v138
	v_exp_f32_e32 v219, v139
	v_pk_add_f32 v[138:139], v[188:189], v[154:155]
	v_pk_add_f32 v[136:137], v[186:187], v[152:153]
	v_cvt_pk_bf16_f32 v132, v186, v187
	v_cvt_pk_bf16_f32 v133, v188, v189
	v_cvt_pk_bf16_f32 v134, v156, v157
	v_cvt_pk_bf16_f32 v135, v158, v159
	v_pk_add_f32 v[150:151], v[158:159], v[138:139]
	v_pk_add_f32 v[148:149], v[156:157], v[136:137]
	v_mfma_f32_32x32x16_bf16 v[96:111], v[182:185], v[172:175], v[96:111]
	v_exp_f32_e32 v152, v140
	v_exp_f32_e32 v153, v141
	v_exp_f32_e32 v154, v142
	v_exp_f32_e32 v155, v143
	v_pk_add_f32 v[142:143], v[218:219], v[150:151]
	v_pk_add_f32 v[140:141], v[216:217], v[148:149]
	v_cvt_pk_bf16_f32 v136, v216, v217
	v_cvt_pk_bf16_f32 v137, v218, v219
	v_cvt_pk_bf16_f32 v138, v152, v153
	v_cvt_pk_bf16_f32 v139, v154, v155
	v_pk_add_f32 v[142:143], v[154:155], v[142:143]
	v_pk_add_f32 v[140:141], v[152:153], v[140:141]
	s_waitcnt vmcnt(4) lgkmcnt(0)
	v_add_f32_e32 v148, v176, v177
	v_add_f32_e32 v149, v178, v179
	v_add_f32_e32 v148, v148, v149
	v_add_f32_e32 v140, v140, v141
	v_add_f32_e32 v141, v142, v143
	s_barrier
	v_add_f32_e32 v148, v180, v148
	v_add_f32_e32 v140, v140, v141
	v_add_f32_e32 v180, v148, v140
	s_add_i32 s47, s47, 2
	s_addk_i32 s41, 0x80
	s_add_i32 s46, s46, 0x8000
	s_add_u32 s98, s98, 0x30000
	s_addc_u32 s99, s99, 0
	s_add_u32 s100, s100, 0x100
	s_addc_u32 s101, s101, 0
	s_add_i32 s49, s58, 0
	s_mov_b32 m0, s49
	s_nop 0
	global_load_lds_dwordx4 v198, s[98:99]
	s_add_i32 m0, s49, 0x400
	s_nop 0
	global_load_lds_dwordx4 v194, s[98:99]
	s_add_i32 s49, s46, 0xffffc000
	s_add_i32 s49, s58, 0x4000
	s_add_i32 m0, s49, 0xc000
	s_nop 0
	global_load_lds_dwordx4 v196, s[100:101]
	s_add_i32 m0, s49, 0xc400
	s_nop 0
	global_load_lds_dwordx4 v192, s[100:101]
	ds_read_b128 v[140:143], v236 offset:16384
	ds_read_b128 v[148:151], v236 offset:20480
	ds_read_b128 v[152:155], v236 offset:24576
	ds_read_b128 v[156:159], v236 offset:28672
	s_waitcnt lgkmcnt(0)
	v_mfma_f32_32x32x16_bf16 v[80:95], v[140:143], v[144:147], v[80:95]
	ds_read_b128 v[140:143], v237 offset:16384
	v_mfma_f32_32x32x16_bf16 v[64:79], v[148:151], v[144:147], v[64:79]
	ds_read_b128 v[148:151], v237 offset:20480
	v_mfma_f32_32x32x16_bf16 v[16:31], v[152:155], v[144:147], v[16:31]
	ds_read_b128 v[152:155], v237 offset:24576
	v_mfma_f32_32x32x16_bf16 v[0:15], v[156:159], v[144:147], v[0:15]
	ds_read_b128 v[144:147], v237 offset:28672
	s_waitcnt lgkmcnt(0)
	v_mfma_f32_32x32x16_bf16 v[80:95], v[140:143], v[128:131], v[80:95]
	ds_read_b128 v[140:143], v238 offset:16384
	v_mfma_f32_32x32x16_bf16 v[64:79], v[148:151], v[128:131], v[64:79]
	ds_read_b128 v[148:151], v238 offset:20480
	v_mfma_f32_32x32x16_bf16 v[16:31], v[152:155], v[128:131], v[16:31]
	ds_read_b128 v[152:155], v238 offset:24576
	v_mfma_f32_32x32x16_bf16 v[0:15], v[144:147], v[128:131], v[0:15]
	ds_read_b128 v[128:131], v238 offset:28672
	s_waitcnt lgkmcnt(0)
	v_mfma_f32_32x32x16_bf16 v[80:95], v[140:143], v[132:135], v[80:95]
	ds_read_b128 v[140:143], v239 offset:16384
	v_mfma_f32_32x32x16_bf16 v[64:79], v[148:151], v[132:135], v[64:79]
	ds_read_b128 v[144:147], v239 offset:20480
	v_mfma_f32_32x32x16_bf16 v[16:31], v[152:155], v[132:135], v[16:31]
	ds_read_b128 v[148:151], v239 offset:24576
	v_mfma_f32_32x32x16_bf16 v[0:15], v[128:131], v[132:135], v[0:15]
	ds_read_b128 v[128:131], v239 offset:28672
	s_waitcnt lgkmcnt(0)
	v_mfma_f32_32x32x16_bf16 v[80:95], v[140:143], v[136:139], v[80:95]
	ds_read_b128 v[132:135], v205 offset:16384
	v_mfma_f32_32x32x16_bf16 v[64:79], v[144:147], v[136:139], v[64:79]
	ds_read_b128 v[140:143], v205 offset:24576
	v_mfma_f32_32x32x16_bf16 v[16:31], v[148:151], v[136:139], v[16:31]
	ds_read_b128 v[176:179], v211 offset:16384
	v_mfma_f32_32x32x16_bf16 v[0:15], v[128:131], v[136:139], v[0:15]
	ds_read_b128 v[182:185], v211 offset:24576
	s_waitcnt lgkmcnt(0)
	v_mfma_f32_32x32x16_bf16 v[144:159], v[132:135], v[160:163], 0
	ds_read_b128 v[186:189], v212 offset:16384
	v_exp_f32_e32 v220, v112
	v_exp_f32_e32 v221, v113
	v_exp_f32_e32 v222, v114
	v_exp_f32_e32 v223, v115
	v_mfma_f32_32x32x16_bf16 v[128:143], v[140:143], v[160:163], 0
	ds_read_b128 v[216:219], v212 offset:24576
	v_exp_f32_e32 v224, v116
	v_exp_f32_e32 v225, v117
	v_exp_f32_e32 v226, v118
	v_exp_f32_e32 v227, v119
	v_mfma_f32_32x32x16_bf16 v[144:159], v[176:179], v[164:167], v[144:159]
	ds_read_b128 v[116:119], v213 offset:16384
	v_exp_f32_e32 v228, v120
	v_exp_f32_e32 v229, v121
	v_exp_f32_e32 v230, v122
	v_exp_f32_e32 v231, v123
	v_cvt_pk_bf16_f32 v112, v220, v221
	v_cvt_pk_bf16_f32 v113, v222, v223
	v_cvt_pk_bf16_f32 v114, v224, v225
	v_cvt_pk_bf16_f32 v115, v226, v227
	v_pk_add_f32 v[122:123], v[226:227], v[222:223]
	v_pk_add_f32 v[120:121], v[224:225], v[220:221]
	v_mfma_f32_32x32x16_bf16 v[128:143], v[182:185], v[164:167], v[128:143]
	ds_read_b128 v[176:179], v213 offset:24576
	v_exp_f32_e32 v124, v124
	v_exp_f32_e32 v125, v125
	v_exp_f32_e32 v126, v126
	v_exp_f32_e32 v127, v127
	s_waitcnt lgkmcnt(0)
	v_mfma_f32_32x32x16_bf16 v[144:159], v[186:189], v[168:171], v[144:159]
	v_add_f32_e64 v122, v230, v122
	v_add_f32_e64 v123, v231, v123
	v_add_f32_e64 v120, v228, v120
	v_add_f32_e64 v121, v229, v121
	v_exp_f32_e32 v182, v96
	v_exp_f32_e32 v183, v97
	v_exp_f32_e32 v184, v98
	v_exp_f32_e32 v185, v99
	v_cvt_pk_bf16_f32 v96, v228, v229
	v_cvt_pk_bf16_f32 v97, v230, v231
	v_cvt_pk_bf16_f32 v98, v124, v125
	v_cvt_pk_bf16_f32 v99, v126, v127
	v_pk_add_f32 v[122:123], v[126:127], v[122:123]
	v_pk_add_f32 v[120:121], v[124:125], v[120:121]
	v_mfma_f32_32x32x16_bf16 v[128:143], v[216:219], v[168:171], v[128:143]
	v_exp_f32_e32 v124, v100
	v_exp_f32_e32 v125, v101
	v_exp_f32_e32 v126, v102
	v_exp_f32_e32 v127, v103
	v_mfma_f32_32x32x16_bf16 v[144:159], v[116:119], v[172:175], v[144:159]
	v_exp_f32_e32 v186, v104
	v_exp_f32_e32 v187, v105
	v_exp_f32_e32 v188, v106
	v_exp_f32_e32 v189, v107
	v_pk_add_f32 v[106:107], v[184:185], v[122:123]
	v_pk_add_f32 v[104:105], v[182:183], v[120:121]
	v_cvt_pk_bf16_f32 v100, v182, v183
	v_cvt_pk_bf16_f32 v101, v184, v185
	v_cvt_pk_bf16_f32 v102, v124, v125
	v_cvt_pk_bf16_f32 v103, v126, v127
	v_pk_add_f32 v[118:119], v[126:127], v[106:107]
	v_pk_add_f32 v[116:117], v[124:125], v[104:105]
	v_mfma_f32_32x32x16_bf16 v[128:143], v[176:179], v[172:175], v[128:143]
	v_exp_f32_e32 v120, v108
	v_exp_f32_e32 v121, v109
	v_exp_f32_e32 v122, v110
	v_exp_f32_e32 v123, v111
	v_pk_add_f32 v[110:111], v[188:189], v[118:119]
	v_pk_add_f32 v[108:109], v[186:187], v[116:117]
	v_cvt_pk_bf16_f32 v104, v186, v187
	v_cvt_pk_bf16_f32 v105, v188, v189
	v_cvt_pk_bf16_f32 v106, v120, v121
	v_cvt_pk_bf16_f32 v107, v122, v123
	v_pk_add_f32 v[178:179], v[122:123], v[110:111]
	v_pk_add_f32 v[176:177], v[120:121], v[108:109]
	s_waitcnt vmcnt(4) lgkmcnt(0)
	s_barrier
	s_add_u32 s70, s98, 0x18000
	s_addc_u32 s71, s99, 0
	s_add_i32 s68, 0x4000, s57
	s_mov_b32 m0, s68
	s_nop 0
	global_load_lds_dwordx4 v198, s[70:71]
	s_add_i32 m0, s68, 0x400
	s_nop 0
	global_load_lds_dwordx4 v194, s[70:71]
	s_add_u32 s2, s100, 0x80
	s_addc_u32 s3, s101, 0
	s_add_i32 s49, s58, 0x8000
	s_add_i32 m0, s49, 0xc000
	s_nop 0
	global_load_lds_dwordx4 v196, s[2:3]
	s_add_i32 m0, s49, 0xc400
	s_nop 0
	global_load_lds_dwordx4 v192, s[2:3]
	s_add_i32 s2, s46, 0xffff4000
	ds_read_b128 v[108:111], v236 offset:32768
	ds_read_b128 v[116:119], v236 offset:36864
	ds_read_b128 v[120:123], v236 offset:40960
	ds_read_b128 v[124:127], v236 offset:45056
	s_waitcnt lgkmcnt(0)
	v_mfma_f32_32x32x16_bf16 v[80:95], v[108:111], v[112:115], v[80:95]
	ds_read_b128 v[108:111], v237 offset:32768
	v_mfma_f32_32x32x16_bf16 v[64:79], v[116:119], v[112:115], v[64:79]
	ds_read_b128 v[116:119], v237 offset:36864
	v_mfma_f32_32x32x16_bf16 v[16:31], v[120:123], v[112:115], v[16:31]
	ds_read_b128 v[120:123], v237 offset:40960
	v_mfma_f32_32x32x16_bf16 v[0:15], v[124:127], v[112:115], v[0:15]
	ds_read_b128 v[112:115], v237 offset:45056
	s_waitcnt lgkmcnt(0)
	v_mfma_f32_32x32x16_bf16 v[80:95], v[108:111], v[96:99], v[80:95]
	ds_read_b128 v[108:111], v238 offset:32768
	v_mfma_f32_32x32x16_bf16 v[64:79], v[116:119], v[96:99], v[64:79]
	ds_read_b128 v[116:119], v238 offset:36864
	v_mfma_f32_32x32x16_bf16 v[16:31], v[120:123], v[96:99], v[16:31]
	ds_read_b128 v[120:123], v238 offset:40960
	v_mfma_f32_32x32x16_bf16 v[0:15], v[112:115], v[96:99], v[0:15]
	ds_read_b128 v[96:99], v238 offset:45056
	s_waitcnt lgkmcnt(0)
	v_mfma_f32_32x32x16_bf16 v[80:95], v[108:111], v[100:103], v[80:95]
	ds_read_b128 v[108:111], v239 offset:32768
	v_mfma_f32_32x32x16_bf16 v[64:79], v[116:119], v[100:103], v[64:79]
	ds_read_b128 v[112:115], v239 offset:36864
	v_mfma_f32_32x32x16_bf16 v[16:31], v[120:123], v[100:103], v[16:31]
	ds_read_b128 v[116:119], v239 offset:40960
	v_mfma_f32_32x32x16_bf16 v[0:15], v[96:99], v[100:103], v[0:15]
	ds_read_b128 v[120:123], v239 offset:45056
	s_waitcnt lgkmcnt(0)
	v_mfma_f32_32x32x16_bf16 v[80:95], v[108:111], v[104:107], v[80:95]
	ds_read_b128 v[96:99], v205 offset:32768
	v_mfma_f32_32x32x16_bf16 v[64:79], v[112:115], v[104:107], v[64:79]
	ds_read_b128 v[100:103], v205 offset:40960
	v_mfma_f32_32x32x16_bf16 v[16:31], v[116:119], v[104:107], v[16:31]
	ds_read_b128 v[182:185], v211 offset:32768
	v_mfma_f32_32x32x16_bf16 v[0:15], v[120:123], v[104:107], v[0:15]
	ds_read_b128 v[186:189], v211 offset:40960
	s_waitcnt lgkmcnt(0)
	v_mfma_f32_32x32x16_bf16 v[112:127], v[96:99], v[160:163], 0
	ds_read_b128 v[216:219], v212 offset:32768
	v_exp_f32_e32 v224, v144
	v_exp_f32_e32 v225, v145
	v_exp_f32_e32 v226, v146
	v_exp_f32_e32 v227, v147
	ds_read_b128 v[220:223], v212 offset:40960
	v_mfma_f32_32x32x16_bf16 v[96:111], v[100:103], v[160:163], 0
	v_exp_f32_e32 v228, v148
	v_exp_f32_e32 v229, v149
	v_exp_f32_e32 v230, v150
	v_exp_f32_e32 v231, v151
	v_mfma_f32_32x32x16_bf16 v[112:127], v[182:185], v[164:167], v[112:127]
	ds_read_b128 v[148:151], v213 offset:32768
	v_exp_f32_e32 v232, v152
	v_exp_f32_e32 v233, v153
	v_exp_f32_e32 v234, v154
	v_exp_f32_e32 v235, v155
	v_cvt_pk_bf16_f32 v144, v224, v225
	v_cvt_pk_bf16_f32 v145, v226, v227
	v_cvt_pk_bf16_f32 v146, v228, v229
	v_cvt_pk_bf16_f32 v147, v230, v231
	v_pk_add_f32 v[154:155], v[230:231], v[226:227]
	v_pk_add_f32 v[152:153], v[228:229], v[224:225]
	v_mfma_f32_32x32x16_bf16 v[96:111], v[186:189], v[164:167], v[96:111]
	ds_read_b128 v[182:185], v213 offset:40960
	v_exp_f32_e32 v156, v156
	v_exp_f32_e32 v157, v157
	v_exp_f32_e32 v158, v158
	v_exp_f32_e32 v159, v159
	s_waitcnt lgkmcnt(0)
	v_mfma_f32_32x32x16_bf16 v[112:127], v[216:219], v[168:171], v[112:127]
	v_add_f32_e64 v154, v234, v154
	v_add_f32_e64 v155, v235, v155
	v_add_f32_e64 v152, v232, v152
	v_add_f32_e64 v153, v233, v153
	v_exp_f32_e32 v186, v128
	v_exp_f32_e32 v187, v129
	v_exp_f32_e32 v188, v130
	v_exp_f32_e32 v189, v131
	v_cvt_pk_bf16_f32 v128, v232, v233
	v_cvt_pk_bf16_f32 v129, v234, v235
	v_cvt_pk_bf16_f32 v130, v156, v157
	v_cvt_pk_bf16_f32 v131, v158, v159
	v_pk_add_f32 v[154:155], v[158:159], v[154:155]
	v_pk_add_f32 v[152:153], v[156:157], v[152:153]
	v_mfma_f32_32x32x16_bf16 v[96:111], v[220:223], v[168:171], v[96:111]
	v_exp_f32_e32 v156, v132
	v_exp_f32_e32 v157, v133
	v_exp_f32_e32 v158, v134
	v_exp_f32_e32 v159, v135
	v_mfma_f32_32x32x16_bf16 v[112:127], v[148:151], v[172:175], v[112:127]
	v_exp_f32_e32 v216, v136
	v_exp_f32_e32 v217, v137
	v_exp_f32_e32 v218, v138
	v_exp_f32_e32 v219, v139
	v_pk_add_f32 v[138:139], v[188:189], v[154:155]
	v_pk_add_f32 v[136:137], v[186:187], v[152:153]
	v_cvt_pk_bf16_f32 v132, v186, v187
	v_cvt_pk_bf16_f32 v133, v188, v189
	v_cvt_pk_bf16_f32 v134, v156, v157
	v_cvt_pk_bf16_f32 v135, v158, v159
	v_pk_add_f32 v[150:151], v[158:159], v[138:139]
	v_pk_add_f32 v[148:149], v[156:157], v[136:137]
	v_mfma_f32_32x32x16_bf16 v[96:111], v[182:185], v[172:175], v[96:111]
	v_exp_f32_e32 v152, v140
	v_exp_f32_e32 v153, v141
	v_exp_f32_e32 v154, v142
	v_exp_f32_e32 v155, v143
	v_pk_add_f32 v[142:143], v[218:219], v[150:151]
	v_pk_add_f32 v[140:141], v[216:217], v[148:149]
	v_cvt_pk_bf16_f32 v136, v216, v217
	v_cvt_pk_bf16_f32 v137, v218, v219
	v_cvt_pk_bf16_f32 v138, v152, v153
	v_cvt_pk_bf16_f32 v139, v154, v155
	v_pk_add_f32 v[142:143], v[154:155], v[142:143]
	v_pk_add_f32 v[140:141], v[152:153], v[140:141]
	s_waitcnt vmcnt(4) lgkmcnt(0)
	v_add_f32_e32 v148, v176, v177
	v_add_f32_e32 v149, v178, v179
	v_add_f32_e32 v148, v148, v149
	v_add_f32_e32 v140, v140, v141
	v_add_f32_e32 v141, v142, v143
	s_barrier
	v_add_f32_e32 v148, v180, v148
	v_add_f32_e32 v140, v140, v141
	v_add_f32_e32 v180, v148, v140
	s_add_i32 s47, s47, 2
	s_addk_i32 s41, 0x80
	s_add_i32 s46, s46, 0x8000
	s_add_u32 s98, s98, 0x30000
	s_addc_u32 s99, s99, 0
	s_add_u32 s100, s100, 0x100
	s_addc_u32 s101, s101, 0
	s_add_i32 s49, s58, 0x8000
	s_mov_b32 m0, s49
	s_nop 0
	global_load_lds_dwordx4 v198, s[98:99]
	s_add_i32 m0, s49, 0x400
	s_nop 0
	global_load_lds_dwordx4 v194, s[98:99]
	s_add_i32 s49, s46, 0xffffc000
	s_add_i32 s49, s58, 0xc000
	s_add_i32 m0, s49, 0xc000
	s_nop 0
	global_load_lds_dwordx4 v196, s[100:101]
	s_add_i32 m0, s49, 0xc400
	s_nop 0
	global_load_lds_dwordx4 v192, s[100:101]
	ds_read_b128 v[140:143], v206 offset:49152
	ds_read_b128 v[148:151], v206 offset:53248
	ds_read_b128 v[152:155], v206 offset:57344
	ds_read_b128 v[156:159], v206 offset:61440
	s_waitcnt lgkmcnt(0)
	v_mfma_f32_32x32x16_bf16 v[80:95], v[140:143], v[144:147], v[80:95]
	ds_read_b128 v[140:143], v207 offset:49152
	v_mfma_f32_32x32x16_bf16 v[64:79], v[148:151], v[144:147], v[64:79]
	ds_read_b128 v[148:151], v207 offset:53248
	v_mfma_f32_32x32x16_bf16 v[16:31], v[152:155], v[144:147], v[16:31]
	ds_read_b128 v[152:155], v207 offset:57344
	v_mfma_f32_32x32x16_bf16 v[0:15], v[156:159], v[144:147], v[0:15]
	ds_read_b128 v[144:147], v207 offset:61440
	s_waitcnt lgkmcnt(0)
	v_mfma_f32_32x32x16_bf16 v[80:95], v[140:143], v[128:131], v[80:95]
	ds_read_b128 v[140:143], v208 offset:49152
	v_mfma_f32_32x32x16_bf16 v[64:79], v[148:151], v[128:131], v[64:79]
	ds_read_b128 v[148:151], v208 offset:53248
	v_mfma_f32_32x32x16_bf16 v[16:31], v[152:155], v[128:131], v[16:31]
	ds_read_b128 v[152:155], v208 offset:57344
	v_mfma_f32_32x32x16_bf16 v[0:15], v[144:147], v[128:131], v[0:15]
	ds_read_b128 v[128:131], v208 offset:61440
	s_waitcnt lgkmcnt(0)
	v_mfma_f32_32x32x16_bf16 v[80:95], v[140:143], v[132:135], v[80:95]
	ds_read_b128 v[140:143], v209 offset:49152
	v_mfma_f32_32x32x16_bf16 v[64:79], v[148:151], v[132:135], v[64:79]
	ds_read_b128 v[144:147], v209 offset:53248
	v_mfma_f32_32x32x16_bf16 v[16:31], v[152:155], v[132:135], v[16:31]
	ds_read_b128 v[148:151], v209 offset:57344
	v_mfma_f32_32x32x16_bf16 v[0:15], v[128:131], v[132:135], v[0:15]
	ds_read_b128 v[128:131], v209 offset:61440
	s_waitcnt lgkmcnt(0)
	v_mfma_f32_32x32x16_bf16 v[80:95], v[140:143], v[136:139], v[80:95]
	ds_read_b128 v[132:135], v205
	v_mfma_f32_32x32x16_bf16 v[64:79], v[144:147], v[136:139], v[64:79]
	ds_read_b128 v[140:143], v205 offset:8192
	v_mfma_f32_32x32x16_bf16 v[16:31], v[148:151], v[136:139], v[16:31]
	ds_read_b128 v[176:179], v211
	v_mfma_f32_32x32x16_bf16 v[0:15], v[128:131], v[136:139], v[0:15]
	ds_read_b128 v[182:185], v211 offset:8192
	s_waitcnt lgkmcnt(0)
	v_mfma_f32_32x32x16_bf16 v[144:159], v[132:135], v[160:163], 0
	ds_read_b128 v[186:189], v212
	v_exp_f32_e32 v220, v112
	v_exp_f32_e32 v221, v113
	v_exp_f32_e32 v222, v114
	v_exp_f32_e32 v223, v115
	v_mfma_f32_32x32x16_bf16 v[128:143], v[140:143], v[160:163], 0
	ds_read_b128 v[216:219], v212 offset:8192
	v_exp_f32_e32 v224, v116
	v_exp_f32_e32 v225, v117
	v_exp_f32_e32 v226, v118
	v_exp_f32_e32 v227, v119
	v_mfma_f32_32x32x16_bf16 v[144:159], v[176:179], v[164:167], v[144:159]
	ds_read_b128 v[116:119], v213
	v_exp_f32_e32 v228, v120
	v_exp_f32_e32 v229, v121
	v_exp_f32_e32 v230, v122
	v_exp_f32_e32 v231, v123
	v_cvt_pk_bf16_f32 v112, v220, v221
	v_cvt_pk_bf16_f32 v113, v222, v223
	v_cvt_pk_bf16_f32 v114, v224, v225
	v_cvt_pk_bf16_f32 v115, v226, v227
	v_pk_add_f32 v[122:123], v[226:227], v[222:223]
	v_pk_add_f32 v[120:121], v[224:225], v[220:221]
	v_mfma_f32_32x32x16_bf16 v[128:143], v[182:185], v[164:167], v[128:143]
	ds_read_b128 v[176:179], v213 offset:8192
	v_exp_f32_e32 v124, v124
	v_exp_f32_e32 v125, v125
	v_exp_f32_e32 v126, v126
	v_exp_f32_e32 v127, v127
	s_waitcnt lgkmcnt(0)
	v_mfma_f32_32x32x16_bf16 v[144:159], v[186:189], v[168:171], v[144:159]
	v_add_f32_e64 v122, v230, v122
	v_add_f32_e64 v123, v231, v123
	v_add_f32_e64 v120, v228, v120
	v_add_f32_e64 v121, v229, v121
	v_exp_f32_e32 v182, v96
	v_exp_f32_e32 v183, v97
	v_exp_f32_e32 v184, v98
	v_exp_f32_e32 v185, v99
	v_cvt_pk_bf16_f32 v96, v228, v229
	v_cvt_pk_bf16_f32 v97, v230, v231
	v_cvt_pk_bf16_f32 v98, v124, v125
	v_cvt_pk_bf16_f32 v99, v126, v127
	v_pk_add_f32 v[122:123], v[126:127], v[122:123]
	v_pk_add_f32 v[120:121], v[124:125], v[120:121]
	v_mfma_f32_32x32x16_bf16 v[128:143], v[216:219], v[168:171], v[128:143]
	v_exp_f32_e32 v124, v100
	v_exp_f32_e32 v125, v101
	v_exp_f32_e32 v126, v102
	v_exp_f32_e32 v127, v103
	v_mfma_f32_32x32x16_bf16 v[144:159], v[116:119], v[172:175], v[144:159]
	v_exp_f32_e32 v186, v104
	v_exp_f32_e32 v187, v105
	v_exp_f32_e32 v188, v106
	v_exp_f32_e32 v189, v107
	v_pk_add_f32 v[106:107], v[184:185], v[122:123]
	v_pk_add_f32 v[104:105], v[182:183], v[120:121]
	v_cvt_pk_bf16_f32 v100, v182, v183
	v_cvt_pk_bf16_f32 v101, v184, v185
	v_cvt_pk_bf16_f32 v102, v124, v125
	v_cvt_pk_bf16_f32 v103, v126, v127
	v_pk_add_f32 v[118:119], v[126:127], v[106:107]
	v_pk_add_f32 v[116:117], v[124:125], v[104:105]
	v_mfma_f32_32x32x16_bf16 v[128:143], v[176:179], v[172:175], v[128:143]
	v_exp_f32_e32 v120, v108
	v_exp_f32_e32 v121, v109
	v_exp_f32_e32 v122, v110
	v_exp_f32_e32 v123, v111
	v_pk_add_f32 v[110:111], v[188:189], v[118:119]
	v_pk_add_f32 v[108:109], v[186:187], v[116:117]
	v_cvt_pk_bf16_f32 v104, v186, v187
	v_cvt_pk_bf16_f32 v105, v188, v189
	v_cvt_pk_bf16_f32 v106, v120, v121
	v_cvt_pk_bf16_f32 v107, v122, v123
	v_pk_add_f32 v[178:179], v[122:123], v[110:111]
	v_pk_add_f32 v[176:177], v[120:121], v[108:109]
	s_waitcnt vmcnt(4) lgkmcnt(0)
	s_barrier
	s_add_u32 s70, s98, 0x18000
	s_addc_u32 s71, s99, 0
	s_add_i32 s68, 0, s57
	s_mov_b32 m0, s68
	s_nop 0
	global_load_lds_dwordx4 v198, s[70:71]
	s_add_i32 m0, s68, 0x400
	s_nop 0
	global_load_lds_dwordx4 v194, s[70:71]
	s_add_u32 s2, s100, 0x80
	s_addc_u32 s3, s101, 0
	s_add_i32 s49, s58, 0
	s_add_i32 m0, s49, 0xc000
	s_nop 0
	global_load_lds_dwordx4 v196, s[2:3]
	s_add_i32 m0, s49, 0xc400
	s_nop 0
	global_load_lds_dwordx4 v192, s[2:3]
	s_add_i32 s2, s46, 0xffff4000
	ds_read_b128 v[108:111], v236
	ds_read_b128 v[116:119], v236 offset:4096
	ds_read_b128 v[120:123], v236 offset:8192
	ds_read_b128 v[124:127], v236 offset:12288
	s_waitcnt lgkmcnt(0)
	v_mfma_f32_32x32x16_bf16 v[80:95], v[108:111], v[112:115], v[80:95]
	ds_read_b128 v[108:111], v237
	v_mfma_f32_32x32x16_bf16 v[64:79], v[116:119], v[112:115], v[64:79]
	ds_read_b128 v[116:119], v237 offset:4096
	v_mfma_f32_32x32x16_bf16 v[16:31], v[120:123], v[112:115], v[16:31]
	ds_read_b128 v[120:123], v237 offset:8192
	v_mfma_f32_32x32x16_bf16 v[0:15], v[124:127], v[112:115], v[0:15]
	ds_read_b128 v[112:115], v237 offset:12288
	s_waitcnt lgkmcnt(0)
	v_mfma_f32_32x32x16_bf16 v[80:95], v[108:111], v[96:99], v[80:95]
	ds_read_b128 v[108:111], v238
	v_mfma_f32_32x32x16_bf16 v[64:79], v[116:119], v[96:99], v[64:79]
	ds_read_b128 v[116:119], v238 offset:4096
	v_mfma_f32_32x32x16_bf16 v[16:31], v[120:123], v[96:99], v[16:31]
	ds_read_b128 v[120:123], v238 offset:8192
	v_mfma_f32_32x32x16_bf16 v[0:15], v[112:115], v[96:99], v[0:15]
	ds_read_b128 v[96:99], v238 offset:12288
	s_waitcnt lgkmcnt(0)
	v_mfma_f32_32x32x16_bf16 v[80:95], v[108:111], v[100:103], v[80:95]
	ds_read_b128 v[108:111], v239
	v_mfma_f32_32x32x16_bf16 v[64:79], v[116:119], v[100:103], v[64:79]
	ds_read_b128 v[112:115], v239 offset:4096
	v_mfma_f32_32x32x16_bf16 v[16:31], v[120:123], v[100:103], v[16:31]
	ds_read_b128 v[116:119], v239 offset:8192
	v_mfma_f32_32x32x16_bf16 v[0:15], v[96:99], v[100:103], v[0:15]
	ds_read_b128 v[120:123], v239 offset:12288
	s_waitcnt lgkmcnt(0)
	v_mfma_f32_32x32x16_bf16 v[80:95], v[108:111], v[104:107], v[80:95]
	ds_read_b128 v[96:99], v205 offset:16384
	v_mfma_f32_32x32x16_bf16 v[64:79], v[112:115], v[104:107], v[64:79]
	ds_read_b128 v[100:103], v205 offset:24576
	v_mfma_f32_32x32x16_bf16 v[16:31], v[116:119], v[104:107], v[16:31]
	ds_read_b128 v[182:185], v211 offset:16384
	v_mfma_f32_32x32x16_bf16 v[0:15], v[120:123], v[104:107], v[0:15]
	ds_read_b128 v[186:189], v211 offset:24576
	s_waitcnt lgkmcnt(0)
	v_mfma_f32_32x32x16_bf16 v[112:127], v[96:99], v[160:163], 0
	ds_read_b128 v[216:219], v212 offset:16384
	v_exp_f32_e32 v224, v144
	v_exp_f32_e32 v225, v145
	v_exp_f32_e32 v226, v146
	v_exp_f32_e32 v227, v147
	ds_read_b128 v[220:223], v212 offset:24576
	v_mfma_f32_32x32x16_bf16 v[96:111], v[100:103], v[160:163], 0
	v_exp_f32_e32 v228, v148
	v_exp_f32_e32 v229, v149
	v_exp_f32_e32 v230, v150
	v_exp_f32_e32 v231, v151
	v_mfma_f32_32x32x16_bf16 v[112:127], v[182:185], v[164:167], v[112:127]
	ds_read_b128 v[148:151], v213 offset:16384
	v_exp_f32_e32 v232, v152
	v_exp_f32_e32 v233, v153
	v_exp_f32_e32 v234, v154
	v_exp_f32_e32 v235, v155
	v_cvt_pk_bf16_f32 v144, v224, v225
	v_cvt_pk_bf16_f32 v145, v226, v227
	v_cvt_pk_bf16_f32 v146, v228, v229
	v_cvt_pk_bf16_f32 v147, v230, v231
	v_pk_add_f32 v[154:155], v[230:231], v[226:227]
	v_pk_add_f32 v[152:153], v[228:229], v[224:225]
	v_mfma_f32_32x32x16_bf16 v[96:111], v[186:189], v[164:167], v[96:111]
	ds_read_b128 v[182:185], v213 offset:24576
	v_exp_f32_e32 v156, v156
	v_exp_f32_e32 v157, v157
	v_exp_f32_e32 v158, v158
	v_exp_f32_e32 v159, v159
	s_waitcnt lgkmcnt(0)
	v_mfma_f32_32x32x16_bf16 v[112:127], v[216:219], v[168:171], v[112:127]
	v_add_f32_e64 v154, v234, v154
	v_add_f32_e64 v155, v235, v155
	v_add_f32_e64 v152, v232, v152
	v_add_f32_e64 v153, v233, v153
	v_exp_f32_e32 v186, v128
	v_exp_f32_e32 v187, v129
	v_exp_f32_e32 v188, v130
	v_exp_f32_e32 v189, v131
	v_cvt_pk_bf16_f32 v128, v232, v233
	v_cvt_pk_bf16_f32 v129, v234, v235
	v_cvt_pk_bf16_f32 v130, v156, v157
	v_cvt_pk_bf16_f32 v131, v158, v159
	v_pk_add_f32 v[154:155], v[158:159], v[154:155]
	v_pk_add_f32 v[152:153], v[156:157], v[152:153]
	v_mfma_f32_32x32x16_bf16 v[96:111], v[220:223], v[168:171], v[96:111]
	v_exp_f32_e32 v156, v132
	v_exp_f32_e32 v157, v133
	v_exp_f32_e32 v158, v134
	v_exp_f32_e32 v159, v135
	v_mfma_f32_32x32x16_bf16 v[112:127], v[148:151], v[172:175], v[112:127]
	v_exp_f32_e32 v216, v136
	v_exp_f32_e32 v217, v137
	v_exp_f32_e32 v218, v138
	v_exp_f32_e32 v219, v139
	v_pk_add_f32 v[138:139], v[188:189], v[154:155]
	v_pk_add_f32 v[136:137], v[186:187], v[152:153]
	v_cvt_pk_bf16_f32 v132, v186, v187
	v_cvt_pk_bf16_f32 v133, v188, v189
	v_cvt_pk_bf16_f32 v134, v156, v157
	v_cvt_pk_bf16_f32 v135, v158, v159
	v_pk_add_f32 v[150:151], v[158:159], v[138:139]
	v_pk_add_f32 v[148:149], v[156:157], v[136:137]
	v_mfma_f32_32x32x16_bf16 v[96:111], v[182:185], v[172:175], v[96:111]
	v_exp_f32_e32 v152, v140
	v_exp_f32_e32 v153, v141
	v_exp_f32_e32 v154, v142
	v_exp_f32_e32 v155, v143
	v_pk_add_f32 v[142:143], v[218:219], v[150:151]
	v_pk_add_f32 v[140:141], v[216:217], v[148:149]
	v_cvt_pk_bf16_f32 v136, v216, v217
	v_cvt_pk_bf16_f32 v137, v218, v219
	v_cvt_pk_bf16_f32 v138, v152, v153
	v_cvt_pk_bf16_f32 v139, v154, v155
	v_pk_add_f32 v[142:143], v[154:155], v[142:143]
	v_pk_add_f32 v[140:141], v[152:153], v[140:141]
	s_waitcnt vmcnt(4) lgkmcnt(0)
	v_add_f32_e32 v148, v176, v177
	v_add_f32_e32 v149, v178, v179
	v_add_f32_e32 v148, v148, v149
	v_add_f32_e32 v140, v140, v141
	v_add_f32_e32 v141, v142, v143
	s_barrier
	v_add_f32_e32 v148, v180, v148
	v_add_f32_e32 v140, v140, v141
	v_add_f32_e32 v180, v148, v140
	s_add_i32 s47, s47, 2
	s_addk_i32 s41, 0x80
	s_add_i32 s46, s46, 0x8000
	s_add_u32 s98, s98, 0x30000
	s_addc_u32 s99, s99, 0
	s_add_u32 s100, s100, 0x100
	s_addc_u32 s101, s101, 0
	s_add_i32 s49, s58, 0x4000
	s_mov_b32 m0, s49
	s_nop 0
	global_load_lds_dwordx4 v198, s[98:99]
	s_add_i32 m0, s49, 0x400
	s_nop 0
	global_load_lds_dwordx4 v194, s[98:99]
	s_add_i32 s49, s46, 0xffffc000
	s_add_i32 s49, s58, 0x4000
	s_add_i32 m0, s49, 0xc000
	s_nop 0
	global_load_lds_dwordx4 v196, s[100:101]
	s_add_i32 m0, s49, 0xc400
	s_nop 0
	global_load_lds_dwordx4 v192, s[100:101]
	ds_read_b128 v[140:143], v236 offset:16384
	ds_read_b128 v[148:151], v236 offset:20480
	ds_read_b128 v[152:155], v236 offset:24576
	ds_read_b128 v[156:159], v236 offset:28672
	s_waitcnt lgkmcnt(0)
	v_mfma_f32_32x32x16_bf16 v[80:95], v[140:143], v[144:147], v[80:95]
	ds_read_b128 v[140:143], v237 offset:16384
	v_mfma_f32_32x32x16_bf16 v[64:79], v[148:151], v[144:147], v[64:79]
	ds_read_b128 v[148:151], v237 offset:20480
	v_mfma_f32_32x32x16_bf16 v[16:31], v[152:155], v[144:147], v[16:31]
	ds_read_b128 v[152:155], v237 offset:24576
	v_mfma_f32_32x32x16_bf16 v[0:15], v[156:159], v[144:147], v[0:15]
	ds_read_b128 v[144:147], v237 offset:28672
	s_waitcnt lgkmcnt(0)
	v_mfma_f32_32x32x16_bf16 v[80:95], v[140:143], v[128:131], v[80:95]
	ds_read_b128 v[140:143], v238 offset:16384
	v_mfma_f32_32x32x16_bf16 v[64:79], v[148:151], v[128:131], v[64:79]
	ds_read_b128 v[148:151], v238 offset:20480
	v_mfma_f32_32x32x16_bf16 v[16:31], v[152:155], v[128:131], v[16:31]
	ds_read_b128 v[152:155], v238 offset:24576
	v_mfma_f32_32x32x16_bf16 v[0:15], v[144:147], v[128:131], v[0:15]
	ds_read_b128 v[128:131], v238 offset:28672
	s_waitcnt lgkmcnt(0)
	v_mfma_f32_32x32x16_bf16 v[80:95], v[140:143], v[132:135], v[80:95]
	ds_read_b128 v[140:143], v239 offset:16384
	v_mfma_f32_32x32x16_bf16 v[64:79], v[148:151], v[132:135], v[64:79]
	ds_read_b128 v[144:147], v239 offset:20480
	v_mfma_f32_32x32x16_bf16 v[16:31], v[152:155], v[132:135], v[16:31]
	ds_read_b128 v[148:151], v239 offset:24576
	v_mfma_f32_32x32x16_bf16 v[0:15], v[128:131], v[132:135], v[0:15]
	ds_read_b128 v[128:131], v239 offset:28672
	s_waitcnt lgkmcnt(0)
	v_mfma_f32_32x32x16_bf16 v[80:95], v[140:143], v[136:139], v[80:95]
	ds_read_b128 v[132:135], v205 offset:32768
	v_mfma_f32_32x32x16_bf16 v[64:79], v[144:147], v[136:139], v[64:79]
	ds_read_b128 v[140:143], v205 offset:40960
	v_mfma_f32_32x32x16_bf16 v[16:31], v[148:151], v[136:139], v[16:31]
	ds_read_b128 v[176:179], v211 offset:32768
	v_mfma_f32_32x32x16_bf16 v[0:15], v[128:131], v[136:139], v[0:15]
	ds_read_b128 v[182:185], v211 offset:40960
	s_waitcnt lgkmcnt(0)
	v_mfma_f32_32x32x16_bf16 v[144:159], v[132:135], v[160:163], 0
	ds_read_b128 v[186:189], v212 offset:32768
	v_exp_f32_e32 v220, v112
	v_exp_f32_e32 v221, v113
	v_exp_f32_e32 v222, v114
	v_exp_f32_e32 v223, v115
	v_mfma_f32_32x32x16_bf16 v[128:143], v[140:143], v[160:163], 0
	ds_read_b128 v[216:219], v212 offset:40960
	v_exp_f32_e32 v224, v116
	v_exp_f32_e32 v225, v117
	v_exp_f32_e32 v226, v118
	v_exp_f32_e32 v227, v119
	v_mfma_f32_32x32x16_bf16 v[144:159], v[176:179], v[164:167], v[144:159]
	ds_read_b128 v[116:119], v213 offset:32768
	v_exp_f32_e32 v228, v120
	v_exp_f32_e32 v229, v121
	v_exp_f32_e32 v230, v122
	v_exp_f32_e32 v231, v123
	v_cvt_pk_bf16_f32 v112, v220, v221
	v_cvt_pk_bf16_f32 v113, v222, v223
	v_cvt_pk_bf16_f32 v114, v224, v225
	v_cvt_pk_bf16_f32 v115, v226, v227
	v_pk_add_f32 v[122:123], v[226:227], v[222:223]
	v_pk_add_f32 v[120:121], v[224:225], v[220:221]
	v_mfma_f32_32x32x16_bf16 v[128:143], v[182:185], v[164:167], v[128:143]
	ds_read_b128 v[176:179], v213 offset:40960
	v_exp_f32_e32 v124, v124
	v_exp_f32_e32 v125, v125
	v_exp_f32_e32 v126, v126
	v_exp_f32_e32 v127, v127
	s_waitcnt lgkmcnt(0)
	v_mfma_f32_32x32x16_bf16 v[144:159], v[186:189], v[168:171], v[144:159]
	v_add_f32_e64 v122, v230, v122
	v_add_f32_e64 v123, v231, v123
	v_add_f32_e64 v120, v228, v120
	v_add_f32_e64 v121, v229, v121
	v_exp_f32_e32 v182, v96
	v_exp_f32_e32 v183, v97
	v_exp_f32_e32 v184, v98
	v_exp_f32_e32 v185, v99
	v_cvt_pk_bf16_f32 v96, v228, v229
	v_cvt_pk_bf16_f32 v97, v230, v231
	v_cvt_pk_bf16_f32 v98, v124, v125
	v_cvt_pk_bf16_f32 v99, v126, v127
	v_pk_add_f32 v[122:123], v[126:127], v[122:123]
	v_pk_add_f32 v[120:121], v[124:125], v[120:121]
	v_mfma_f32_32x32x16_bf16 v[128:143], v[216:219], v[168:171], v[128:143]
	v_exp_f32_e32 v124, v100
	v_exp_f32_e32 v125, v101
	v_exp_f32_e32 v126, v102
	v_exp_f32_e32 v127, v103
	v_mfma_f32_32x32x16_bf16 v[144:159], v[116:119], v[172:175], v[144:159]
	v_exp_f32_e32 v186, v104
	v_exp_f32_e32 v187, v105
	v_exp_f32_e32 v188, v106
	v_exp_f32_e32 v189, v107
	v_pk_add_f32 v[106:107], v[184:185], v[122:123]
	v_pk_add_f32 v[104:105], v[182:183], v[120:121]
	v_cvt_pk_bf16_f32 v100, v182, v183
	v_cvt_pk_bf16_f32 v101, v184, v185
	v_cvt_pk_bf16_f32 v102, v124, v125
	v_cvt_pk_bf16_f32 v103, v126, v127
	v_pk_add_f32 v[118:119], v[126:127], v[106:107]
	v_pk_add_f32 v[116:117], v[124:125], v[104:105]
	v_mfma_f32_32x32x16_bf16 v[128:143], v[176:179], v[172:175], v[128:143]
	v_exp_f32_e32 v120, v108
	v_exp_f32_e32 v121, v109
	v_exp_f32_e32 v122, v110
	v_exp_f32_e32 v123, v111
	v_pk_add_f32 v[110:111], v[188:189], v[118:119]
	v_pk_add_f32 v[108:109], v[186:187], v[116:117]
	v_cvt_pk_bf16_f32 v104, v186, v187
	v_cvt_pk_bf16_f32 v105, v188, v189
	v_cvt_pk_bf16_f32 v106, v120, v121
	v_cvt_pk_bf16_f32 v107, v122, v123
	v_pk_add_f32 v[178:179], v[122:123], v[110:111]
	v_pk_add_f32 v[176:177], v[120:121], v[108:109]
	s_waitcnt vmcnt(4) lgkmcnt(0)
	s_barrier
	s_add_u32 s70, s98, 0x18000
	s_addc_u32 s71, s99, 0
	s_add_i32 s68, 0x8000, s57
	s_mov_b32 m0, s68
	s_nop 0
	global_load_lds_dwordx4 v198, s[70:71]
	s_add_i32 m0, s68, 0x400
	s_nop 0
	global_load_lds_dwordx4 v194, s[70:71]
	s_add_u32 s2, s100, 0x80
	s_addc_u32 s3, s101, 0
	s_add_i32 s49, s58, 0x8000
	s_add_i32 m0, s49, 0xc000
	s_nop 0
	global_load_lds_dwordx4 v196, s[2:3]
	s_add_i32 m0, s49, 0xc400
	s_nop 0
	global_load_lds_dwordx4 v192, s[2:3]
	s_add_i32 s2, s46, 0xffff4000
	ds_read_b128 v[108:111], v236 offset:32768
	ds_read_b128 v[116:119], v236 offset:36864
	ds_read_b128 v[120:123], v236 offset:40960
	ds_read_b128 v[124:127], v236 offset:45056
	s_waitcnt lgkmcnt(0)
	v_mfma_f32_32x32x16_bf16 v[80:95], v[108:111], v[112:115], v[80:95]
	ds_read_b128 v[108:111], v237 offset:32768
	v_mfma_f32_32x32x16_bf16 v[64:79], v[116:119], v[112:115], v[64:79]
	ds_read_b128 v[116:119], v237 offset:36864
	v_mfma_f32_32x32x16_bf16 v[16:31], v[120:123], v[112:115], v[16:31]
	ds_read_b128 v[120:123], v237 offset:40960
	v_mfma_f32_32x32x16_bf16 v[0:15], v[124:127], v[112:115], v[0:15]
	ds_read_b128 v[112:115], v237 offset:45056
	s_waitcnt lgkmcnt(0)
	v_mfma_f32_32x32x16_bf16 v[80:95], v[108:111], v[96:99], v[80:95]
	ds_read_b128 v[108:111], v238 offset:32768
	v_mfma_f32_32x32x16_bf16 v[64:79], v[116:119], v[96:99], v[64:79]
	ds_read_b128 v[116:119], v238 offset:36864
	v_mfma_f32_32x32x16_bf16 v[16:31], v[120:123], v[96:99], v[16:31]
	ds_read_b128 v[120:123], v238 offset:40960
	v_mfma_f32_32x32x16_bf16 v[0:15], v[112:115], v[96:99], v[0:15]
	ds_read_b128 v[96:99], v238 offset:45056
	s_waitcnt lgkmcnt(0)
	v_mfma_f32_32x32x16_bf16 v[80:95], v[108:111], v[100:103], v[80:95]
	ds_read_b128 v[108:111], v239 offset:32768
	v_mfma_f32_32x32x16_bf16 v[64:79], v[116:119], v[100:103], v[64:79]
	ds_read_b128 v[112:115], v239 offset:36864
	v_mfma_f32_32x32x16_bf16 v[16:31], v[120:123], v[100:103], v[16:31]
	ds_read_b128 v[116:119], v239 offset:40960
	v_mfma_f32_32x32x16_bf16 v[0:15], v[96:99], v[100:103], v[0:15]
	ds_read_b128 v[120:123], v239 offset:45056
	s_waitcnt lgkmcnt(0)
	v_mfma_f32_32x32x16_bf16 v[80:95], v[108:111], v[104:107], v[80:95]
	ds_read_b128 v[96:99], v205
	v_mfma_f32_32x32x16_bf16 v[64:79], v[112:115], v[104:107], v[64:79]
	ds_read_b128 v[100:103], v205 offset:8192
	v_mfma_f32_32x32x16_bf16 v[16:31], v[116:119], v[104:107], v[16:31]
	ds_read_b128 v[182:185], v211
	v_mfma_f32_32x32x16_bf16 v[0:15], v[120:123], v[104:107], v[0:15]
	ds_read_b128 v[186:189], v211 offset:8192
	s_waitcnt lgkmcnt(0)
	v_mfma_f32_32x32x16_bf16 v[112:127], v[96:99], v[160:163], 0
	ds_read_b128 v[216:219], v212
	v_exp_f32_e32 v224, v144
	v_exp_f32_e32 v225, v145
	v_exp_f32_e32 v226, v146
	v_exp_f32_e32 v227, v147
	ds_read_b128 v[220:223], v212 offset:8192
	v_mfma_f32_32x32x16_bf16 v[96:111], v[100:103], v[160:163], 0
	v_exp_f32_e32 v228, v148
	v_exp_f32_e32 v229, v149
	v_exp_f32_e32 v230, v150
	v_exp_f32_e32 v231, v151
	v_mfma_f32_32x32x16_bf16 v[112:127], v[182:185], v[164:167], v[112:127]
	ds_read_b128 v[148:151], v213
	v_exp_f32_e32 v232, v152
	v_exp_f32_e32 v233, v153
	v_exp_f32_e32 v234, v154
	v_exp_f32_e32 v235, v155
	v_cvt_pk_bf16_f32 v144, v224, v225
	v_cvt_pk_bf16_f32 v145, v226, v227
	v_cvt_pk_bf16_f32 v146, v228, v229
	v_cvt_pk_bf16_f32 v147, v230, v231
	v_pk_add_f32 v[154:155], v[230:231], v[226:227]
	v_pk_add_f32 v[152:153], v[228:229], v[224:225]
	v_mfma_f32_32x32x16_bf16 v[96:111], v[186:189], v[164:167], v[96:111]
	ds_read_b128 v[182:185], v213 offset:8192
	v_exp_f32_e32 v156, v156
	v_exp_f32_e32 v157, v157
	v_exp_f32_e32 v158, v158
	v_exp_f32_e32 v159, v159
	s_waitcnt lgkmcnt(0)
	v_mfma_f32_32x32x16_bf16 v[112:127], v[216:219], v[168:171], v[112:127]
	v_add_f32_e64 v154, v234, v154
	v_add_f32_e64 v155, v235, v155
	v_add_f32_e64 v152, v232, v152
	v_add_f32_e64 v153, v233, v153
	v_exp_f32_e32 v186, v128
	v_exp_f32_e32 v187, v129
	v_exp_f32_e32 v188, v130
	v_exp_f32_e32 v189, v131
	v_cvt_pk_bf16_f32 v128, v232, v233
	v_cvt_pk_bf16_f32 v129, v234, v235
	v_cvt_pk_bf16_f32 v130, v156, v157
	v_cvt_pk_bf16_f32 v131, v158, v159
	v_pk_add_f32 v[154:155], v[158:159], v[154:155]
	v_pk_add_f32 v[152:153], v[156:157], v[152:153]
	v_mfma_f32_32x32x16_bf16 v[96:111], v[220:223], v[168:171], v[96:111]
	v_exp_f32_e32 v156, v132
	v_exp_f32_e32 v157, v133
	v_exp_f32_e32 v158, v134
	v_exp_f32_e32 v159, v135
	v_mfma_f32_32x32x16_bf16 v[112:127], v[148:151], v[172:175], v[112:127]
	v_exp_f32_e32 v216, v136
	v_exp_f32_e32 v217, v137
	v_exp_f32_e32 v218, v138
	v_exp_f32_e32 v219, v139
	v_pk_add_f32 v[138:139], v[188:189], v[154:155]
	v_pk_add_f32 v[136:137], v[186:187], v[152:153]
	v_cvt_pk_bf16_f32 v132, v186, v187
	v_cvt_pk_bf16_f32 v133, v188, v189
	v_cvt_pk_bf16_f32 v134, v156, v157
	v_cvt_pk_bf16_f32 v135, v158, v159
	v_pk_add_f32 v[150:151], v[158:159], v[138:139]
	v_pk_add_f32 v[148:149], v[156:157], v[136:137]
	v_mfma_f32_32x32x16_bf16 v[96:111], v[182:185], v[172:175], v[96:111]
	v_exp_f32_e32 v152, v140
	v_exp_f32_e32 v153, v141
	v_exp_f32_e32 v154, v142
	v_exp_f32_e32 v155, v143
	v_pk_add_f32 v[142:143], v[218:219], v[150:151]
	v_pk_add_f32 v[140:141], v[216:217], v[148:149]
	v_cvt_pk_bf16_f32 v136, v216, v217
	v_cvt_pk_bf16_f32 v137, v218, v219
	v_cvt_pk_bf16_f32 v138, v152, v153
	v_cvt_pk_bf16_f32 v139, v154, v155
	v_pk_add_f32 v[142:143], v[154:155], v[142:143]
	v_pk_add_f32 v[140:141], v[152:153], v[140:141]
	s_waitcnt vmcnt(4) lgkmcnt(0)
	v_add_f32_e32 v148, v176, v177
	v_add_f32_e32 v149, v178, v179
	v_add_f32_e32 v148, v148, v149
	v_add_f32_e32 v140, v140, v141
	v_add_f32_e32 v141, v142, v143
	s_barrier
	v_add_f32_e32 v148, v180, v148
	v_add_f32_e32 v140, v140, v141
	v_add_f32_e32 v180, v148, v140
	s_add_i32 s47, s47, 2
	s_addk_i32 s41, 0x80
	s_add_i32 s46, s46, 0x8000
	s_add_u32 s98, s98, 0x30000
	s_addc_u32 s99, s99, 0
	s_add_u32 s100, s100, 0x100
	s_addc_u32 s101, s101, 0
	s_add_i32 s49, s58, 0
	s_mov_b32 m0, s49
	s_nop 0
	global_load_lds_dwordx4 v198, s[98:99]
	s_add_i32 m0, s49, 0x400
	s_nop 0
	global_load_lds_dwordx4 v194, s[98:99]
	s_add_i32 s49, s46, 0xffffc000
	s_add_i32 s49, s58, 0xc000
	s_add_i32 m0, s49, 0xc000
	s_nop 0
	global_load_lds_dwordx4 v196, s[100:101]
	s_add_i32 m0, s49, 0xc400
	s_nop 0
	global_load_lds_dwordx4 v192, s[100:101]
	ds_read_b128 v[140:143], v206 offset:49152
	ds_read_b128 v[148:151], v206 offset:53248
	ds_read_b128 v[152:155], v206 offset:57344
	ds_read_b128 v[156:159], v206 offset:61440
	s_waitcnt lgkmcnt(0)
	v_mfma_f32_32x32x16_bf16 v[80:95], v[140:143], v[144:147], v[80:95]
	ds_read_b128 v[140:143], v207 offset:49152
	v_mfma_f32_32x32x16_bf16 v[64:79], v[148:151], v[144:147], v[64:79]
	ds_read_b128 v[148:151], v207 offset:53248
	v_mfma_f32_32x32x16_bf16 v[16:31], v[152:155], v[144:147], v[16:31]
	ds_read_b128 v[152:155], v207 offset:57344
	v_mfma_f32_32x32x16_bf16 v[0:15], v[156:159], v[144:147], v[0:15]
	ds_read_b128 v[144:147], v207 offset:61440
	s_waitcnt lgkmcnt(0)
	v_mfma_f32_32x32x16_bf16 v[80:95], v[140:143], v[128:131], v[80:95]
	ds_read_b128 v[140:143], v208 offset:49152
	v_mfma_f32_32x32x16_bf16 v[64:79], v[148:151], v[128:131], v[64:79]
	ds_read_b128 v[148:151], v208 offset:53248
	v_mfma_f32_32x32x16_bf16 v[16:31], v[152:155], v[128:131], v[16:31]
	ds_read_b128 v[152:155], v208 offset:57344
	v_mfma_f32_32x32x16_bf16 v[0:15], v[144:147], v[128:131], v[0:15]
	ds_read_b128 v[128:131], v208 offset:61440
	s_waitcnt lgkmcnt(0)
	v_mfma_f32_32x32x16_bf16 v[80:95], v[140:143], v[132:135], v[80:95]
	ds_read_b128 v[140:143], v209 offset:49152
	v_mfma_f32_32x32x16_bf16 v[64:79], v[148:151], v[132:135], v[64:79]
	ds_read_b128 v[144:147], v209 offset:53248
	v_mfma_f32_32x32x16_bf16 v[16:31], v[152:155], v[132:135], v[16:31]
	ds_read_b128 v[148:151], v209 offset:57344
	v_mfma_f32_32x32x16_bf16 v[0:15], v[128:131], v[132:135], v[0:15]
	ds_read_b128 v[128:131], v209 offset:61440
	s_waitcnt lgkmcnt(0)
	v_mfma_f32_32x32x16_bf16 v[80:95], v[140:143], v[136:139], v[80:95]
	ds_read_b128 v[132:135], v205 offset:16384
	v_mfma_f32_32x32x16_bf16 v[64:79], v[144:147], v[136:139], v[64:79]
	ds_read_b128 v[140:143], v205 offset:24576
	v_mfma_f32_32x32x16_bf16 v[16:31], v[148:151], v[136:139], v[16:31]
	ds_read_b128 v[176:179], v211 offset:16384
	v_mfma_f32_32x32x16_bf16 v[0:15], v[128:131], v[136:139], v[0:15]
	ds_read_b128 v[182:185], v211 offset:24576
	s_waitcnt lgkmcnt(0)
	v_mfma_f32_32x32x16_bf16 v[144:159], v[132:135], v[160:163], 0
	ds_read_b128 v[186:189], v212 offset:16384
	v_exp_f32_e32 v220, v112
	v_exp_f32_e32 v221, v113
	v_exp_f32_e32 v222, v114
	v_exp_f32_e32 v223, v115
	v_mfma_f32_32x32x16_bf16 v[128:143], v[140:143], v[160:163], 0
	ds_read_b128 v[216:219], v212 offset:24576
	v_exp_f32_e32 v224, v116
	v_exp_f32_e32 v225, v117
	v_exp_f32_e32 v226, v118
	v_exp_f32_e32 v227, v119
	v_mfma_f32_32x32x16_bf16 v[144:159], v[176:179], v[164:167], v[144:159]
	ds_read_b128 v[116:119], v213 offset:16384
	v_exp_f32_e32 v228, v120
	v_exp_f32_e32 v229, v121
	v_exp_f32_e32 v230, v122
	v_exp_f32_e32 v231, v123
	v_cvt_pk_bf16_f32 v112, v220, v221
	v_cvt_pk_bf16_f32 v113, v222, v223
	v_cvt_pk_bf16_f32 v114, v224, v225
	v_cvt_pk_bf16_f32 v115, v226, v227
	v_pk_add_f32 v[122:123], v[226:227], v[222:223]
	v_pk_add_f32 v[120:121], v[224:225], v[220:221]
	v_mfma_f32_32x32x16_bf16 v[128:143], v[182:185], v[164:167], v[128:143]
	ds_read_b128 v[176:179], v213 offset:24576
	v_exp_f32_e32 v124, v124
	v_exp_f32_e32 v125, v125
	v_exp_f32_e32 v126, v126
	v_exp_f32_e32 v127, v127
	s_waitcnt lgkmcnt(0)
	v_mfma_f32_32x32x16_bf16 v[144:159], v[186:189], v[168:171], v[144:159]
	v_add_f32_e64 v122, v230, v122
	v_add_f32_e64 v123, v231, v123
	v_add_f32_e64 v120, v228, v120
	v_add_f32_e64 v121, v229, v121
	v_exp_f32_e32 v182, v96
	v_exp_f32_e32 v183, v97
	v_exp_f32_e32 v184, v98
	v_exp_f32_e32 v185, v99
	v_cvt_pk_bf16_f32 v96, v228, v229
	v_cvt_pk_bf16_f32 v97, v230, v231
	v_cvt_pk_bf16_f32 v98, v124, v125
	v_cvt_pk_bf16_f32 v99, v126, v127
	v_pk_add_f32 v[122:123], v[126:127], v[122:123]
	v_pk_add_f32 v[120:121], v[124:125], v[120:121]
	v_mfma_f32_32x32x16_bf16 v[128:143], v[216:219], v[168:171], v[128:143]
	v_exp_f32_e32 v124, v100
	v_exp_f32_e32 v125, v101
	v_exp_f32_e32 v126, v102
	v_exp_f32_e32 v127, v103
	v_mfma_f32_32x32x16_bf16 v[144:159], v[116:119], v[172:175], v[144:159]
	v_exp_f32_e32 v186, v104
	v_exp_f32_e32 v187, v105
	v_exp_f32_e32 v188, v106
	v_exp_f32_e32 v189, v107
	v_pk_add_f32 v[106:107], v[184:185], v[122:123]
	v_pk_add_f32 v[104:105], v[182:183], v[120:121]
	v_cvt_pk_bf16_f32 v100, v182, v183
	v_cvt_pk_bf16_f32 v101, v184, v185
	v_cvt_pk_bf16_f32 v102, v124, v125
	v_cvt_pk_bf16_f32 v103, v126, v127
	v_pk_add_f32 v[118:119], v[126:127], v[106:107]
	v_pk_add_f32 v[116:117], v[124:125], v[104:105]
	v_mfma_f32_32x32x16_bf16 v[128:143], v[176:179], v[172:175], v[128:143]
	v_exp_f32_e32 v120, v108
	v_exp_f32_e32 v121, v109
	v_exp_f32_e32 v122, v110
	v_exp_f32_e32 v123, v111
	v_pk_add_f32 v[110:111], v[188:189], v[118:119]
	v_pk_add_f32 v[108:109], v[186:187], v[116:117]
	v_cvt_pk_bf16_f32 v104, v186, v187
	v_cvt_pk_bf16_f32 v105, v188, v189
	v_cvt_pk_bf16_f32 v106, v120, v121
	v_cvt_pk_bf16_f32 v107, v122, v123
	v_pk_add_f32 v[178:179], v[122:123], v[110:111]
	v_pk_add_f32 v[176:177], v[120:121], v[108:109]
	s_waitcnt vmcnt(4) lgkmcnt(0)
	s_barrier
	s_add_u32 s70, s98, 0x18000
	s_addc_u32 s71, s99, 0
	s_add_i32 s68, 0x4000, s57
	s_mov_b32 m0, s68
	s_nop 0
	global_load_lds_dwordx4 v198, s[70:71]
	s_add_i32 m0, s68, 0x400
	s_nop 0
	global_load_lds_dwordx4 v194, s[70:71]
	s_add_u32 s2, s100, 0x80
	s_addc_u32 s3, s101, 0
	s_add_i32 s49, s58, 0
	s_add_i32 m0, s49, 0xc000
	s_nop 0
	global_load_lds_dwordx4 v196, s[2:3]
	s_add_i32 m0, s49, 0xc400
	s_nop 0
	global_load_lds_dwordx4 v192, s[2:3]
	s_add_i32 s2, s46, 0xffff4000
	ds_read_b128 v[108:111], v236
	ds_read_b128 v[116:119], v236 offset:4096
	ds_read_b128 v[120:123], v236 offset:8192
	ds_read_b128 v[124:127], v236 offset:12288
	s_waitcnt lgkmcnt(0)
	v_mfma_f32_32x32x16_bf16 v[80:95], v[108:111], v[112:115], v[80:95]
	ds_read_b128 v[108:111], v237
	v_mfma_f32_32x32x16_bf16 v[64:79], v[116:119], v[112:115], v[64:79]
	ds_read_b128 v[116:119], v237 offset:4096
	v_mfma_f32_32x32x16_bf16 v[16:31], v[120:123], v[112:115], v[16:31]
	ds_read_b128 v[120:123], v237 offset:8192
	v_mfma_f32_32x32x16_bf16 v[0:15], v[124:127], v[112:115], v[0:15]
	ds_read_b128 v[112:115], v237 offset:12288
	s_waitcnt lgkmcnt(0)
	v_mfma_f32_32x32x16_bf16 v[80:95], v[108:111], v[96:99], v[80:95]
	ds_read_b128 v[108:111], v238
	v_mfma_f32_32x32x16_bf16 v[64:79], v[116:119], v[96:99], v[64:79]
	ds_read_b128 v[116:119], v238 offset:4096
	v_mfma_f32_32x32x16_bf16 v[16:31], v[120:123], v[96:99], v[16:31]
	ds_read_b128 v[120:123], v238 offset:8192
	v_mfma_f32_32x32x16_bf16 v[0:15], v[112:115], v[96:99], v[0:15]
	ds_read_b128 v[96:99], v238 offset:12288
	s_waitcnt lgkmcnt(0)
	v_mfma_f32_32x32x16_bf16 v[80:95], v[108:111], v[100:103], v[80:95]
	ds_read_b128 v[108:111], v239
	v_mfma_f32_32x32x16_bf16 v[64:79], v[116:119], v[100:103], v[64:79]
	ds_read_b128 v[112:115], v239 offset:4096
	v_mfma_f32_32x32x16_bf16 v[16:31], v[120:123], v[100:103], v[16:31]
	ds_read_b128 v[116:119], v239 offset:8192
	v_mfma_f32_32x32x16_bf16 v[0:15], v[96:99], v[100:103], v[0:15]
	ds_read_b128 v[120:123], v239 offset:12288
	s_waitcnt lgkmcnt(0)
	v_mfma_f32_32x32x16_bf16 v[80:95], v[108:111], v[104:107], v[80:95]
	ds_read_b128 v[96:99], v205 offset:32768
	v_mfma_f32_32x32x16_bf16 v[64:79], v[112:115], v[104:107], v[64:79]
	ds_read_b128 v[100:103], v205 offset:40960
	v_mfma_f32_32x32x16_bf16 v[16:31], v[116:119], v[104:107], v[16:31]
	ds_read_b128 v[182:185], v211 offset:32768
	v_mfma_f32_32x32x16_bf16 v[0:15], v[120:123], v[104:107], v[0:15]
	ds_read_b128 v[186:189], v211 offset:40960
	s_waitcnt lgkmcnt(0)
	v_mfma_f32_32x32x16_bf16 v[112:127], v[96:99], v[160:163], 0
	ds_read_b128 v[216:219], v212 offset:32768
	v_exp_f32_e32 v224, v144
	v_exp_f32_e32 v225, v145
	v_exp_f32_e32 v226, v146
	v_exp_f32_e32 v227, v147
	ds_read_b128 v[220:223], v212 offset:40960
	v_mfma_f32_32x32x16_bf16 v[96:111], v[100:103], v[160:163], 0
	v_exp_f32_e32 v228, v148
	v_exp_f32_e32 v229, v149
	v_exp_f32_e32 v230, v150
	v_exp_f32_e32 v231, v151
	v_mfma_f32_32x32x16_bf16 v[112:127], v[182:185], v[164:167], v[112:127]
	ds_read_b128 v[148:151], v213 offset:32768
	v_exp_f32_e32 v232, v152
	v_exp_f32_e32 v233, v153
	v_exp_f32_e32 v234, v154
	v_exp_f32_e32 v235, v155
	v_cvt_pk_bf16_f32 v144, v224, v225
	v_cvt_pk_bf16_f32 v145, v226, v227
	v_cvt_pk_bf16_f32 v146, v228, v229
	v_cvt_pk_bf16_f32 v147, v230, v231
	v_pk_add_f32 v[154:155], v[230:231], v[226:227]
	v_pk_add_f32 v[152:153], v[228:229], v[224:225]
	v_mfma_f32_32x32x16_bf16 v[96:111], v[186:189], v[164:167], v[96:111]
	ds_read_b128 v[182:185], v213 offset:40960
	v_exp_f32_e32 v156, v156
	v_exp_f32_e32 v157, v157
	v_exp_f32_e32 v158, v158
	v_exp_f32_e32 v159, v159
	s_waitcnt lgkmcnt(0)
	v_mfma_f32_32x32x16_bf16 v[112:127], v[216:219], v[168:171], v[112:127]
	v_add_f32_e64 v154, v234, v154
	v_add_f32_e64 v155, v235, v155
	v_add_f32_e64 v152, v232, v152
	v_add_f32_e64 v153, v233, v153
	v_exp_f32_e32 v186, v128
	v_exp_f32_e32 v187, v129
	v_exp_f32_e32 v188, v130
	v_exp_f32_e32 v189, v131
	v_cvt_pk_bf16_f32 v128, v232, v233
	v_cvt_pk_bf16_f32 v129, v234, v235
	v_cvt_pk_bf16_f32 v130, v156, v157
	v_cvt_pk_bf16_f32 v131, v158, v159
	v_pk_add_f32 v[154:155], v[158:159], v[154:155]
	v_pk_add_f32 v[152:153], v[156:157], v[152:153]
	v_mfma_f32_32x32x16_bf16 v[96:111], v[220:223], v[168:171], v[96:111]
	v_exp_f32_e32 v156, v132
	v_exp_f32_e32 v157, v133
	v_exp_f32_e32 v158, v134
	v_exp_f32_e32 v159, v135
	v_mfma_f32_32x32x16_bf16 v[112:127], v[148:151], v[172:175], v[112:127]
	v_exp_f32_e32 v216, v136
	v_exp_f32_e32 v217, v137
	v_exp_f32_e32 v218, v138
	v_exp_f32_e32 v219, v139
	v_pk_add_f32 v[138:139], v[188:189], v[154:155]
	v_pk_add_f32 v[136:137], v[186:187], v[152:153]
	v_cvt_pk_bf16_f32 v132, v186, v187
	v_cvt_pk_bf16_f32 v133, v188, v189
	v_cvt_pk_bf16_f32 v134, v156, v157
	v_cvt_pk_bf16_f32 v135, v158, v159
	v_pk_add_f32 v[150:151], v[158:159], v[138:139]
	v_pk_add_f32 v[148:149], v[156:157], v[136:137]
	v_mfma_f32_32x32x16_bf16 v[96:111], v[182:185], v[172:175], v[96:111]
	v_exp_f32_e32 v152, v140
	v_exp_f32_e32 v153, v141
	v_exp_f32_e32 v154, v142
	v_exp_f32_e32 v155, v143
	v_pk_add_f32 v[142:143], v[218:219], v[150:151]
	v_pk_add_f32 v[140:141], v[216:217], v[148:149]
	v_cvt_pk_bf16_f32 v136, v216, v217
	v_cvt_pk_bf16_f32 v137, v218, v219
	v_cvt_pk_bf16_f32 v138, v152, v153
	v_cvt_pk_bf16_f32 v139, v154, v155
	v_pk_add_f32 v[142:143], v[154:155], v[142:143]
	v_pk_add_f32 v[140:141], v[152:153], v[140:141]
	s_waitcnt vmcnt(4) lgkmcnt(0)
	v_add_f32_e32 v148, v176, v177
	v_add_f32_e32 v149, v178, v179
	v_add_f32_e32 v148, v148, v149
	v_add_f32_e32 v140, v140, v141
	v_add_f32_e32 v141, v142, v143
	s_barrier
	v_add_f32_e32 v148, v180, v148
	v_add_f32_e32 v140, v140, v141
	v_add_f32_e32 v180, v148, v140
	s_add_i32 s47, s47, 2
	s_addk_i32 s41, 0x80
	s_add_i32 s46, s46, 0x8000
	s_add_u32 s98, s98, 0x30000
	s_addc_u32 s99, s99, 0
	s_add_u32 s100, s100, 0x100
	s_addc_u32 s101, s101, 0
	s_add_i32 s49, s58, 0x8000
	s_mov_b32 m0, s49
	s_nop 0
	global_load_lds_dwordx4 v198, s[98:99]
	s_add_i32 m0, s49, 0x400
	s_nop 0
	global_load_lds_dwordx4 v194, s[98:99]
	s_add_i32 s49, s46, 0xffffc000
	s_add_i32 s49, s58, 0x4000
	s_add_i32 m0, s49, 0xc000
	s_nop 0
	global_load_lds_dwordx4 v196, s[100:101]
	s_add_i32 m0, s49, 0xc400
	s_nop 0
	global_load_lds_dwordx4 v192, s[100:101]
	ds_read_b128 v[140:143], v236 offset:16384
	ds_read_b128 v[148:151], v236 offset:20480
	ds_read_b128 v[152:155], v236 offset:24576
	ds_read_b128 v[156:159], v236 offset:28672
	s_waitcnt lgkmcnt(0)
	v_mfma_f32_32x32x16_bf16 v[80:95], v[140:143], v[144:147], v[80:95]
	ds_read_b128 v[140:143], v237 offset:16384
	v_mfma_f32_32x32x16_bf16 v[64:79], v[148:151], v[144:147], v[64:79]
	ds_read_b128 v[148:151], v237 offset:20480
	v_mfma_f32_32x32x16_bf16 v[16:31], v[152:155], v[144:147], v[16:31]
	ds_read_b128 v[152:155], v237 offset:24576
	v_mfma_f32_32x32x16_bf16 v[0:15], v[156:159], v[144:147], v[0:15]
	ds_read_b128 v[144:147], v237 offset:28672
	s_waitcnt lgkmcnt(0)
	v_mfma_f32_32x32x16_bf16 v[80:95], v[140:143], v[128:131], v[80:95]
	ds_read_b128 v[140:143], v238 offset:16384
	v_mfma_f32_32x32x16_bf16 v[64:79], v[148:151], v[128:131], v[64:79]
	ds_read_b128 v[148:151], v238 offset:20480
	v_mfma_f32_32x32x16_bf16 v[16:31], v[152:155], v[128:131], v[16:31]
	ds_read_b128 v[152:155], v238 offset:24576
	v_mfma_f32_32x32x16_bf16 v[0:15], v[144:147], v[128:131], v[0:15]
	ds_read_b128 v[128:131], v238 offset:28672
	s_waitcnt lgkmcnt(0)
	v_mfma_f32_32x32x16_bf16 v[80:95], v[140:143], v[132:135], v[80:95]
	ds_read_b128 v[140:143], v239 offset:16384
	v_mfma_f32_32x32x16_bf16 v[64:79], v[148:151], v[132:135], v[64:79]
	ds_read_b128 v[144:147], v239 offset:20480
	v_mfma_f32_32x32x16_bf16 v[16:31], v[152:155], v[132:135], v[16:31]
	ds_read_b128 v[148:151], v239 offset:24576
	v_mfma_f32_32x32x16_bf16 v[0:15], v[128:131], v[132:135], v[0:15]
	ds_read_b128 v[128:131], v239 offset:28672
	s_waitcnt lgkmcnt(0)
	v_mfma_f32_32x32x16_bf16 v[80:95], v[140:143], v[136:139], v[80:95]
	ds_read_b128 v[132:135], v205
	v_mfma_f32_32x32x16_bf16 v[64:79], v[144:147], v[136:139], v[64:79]
	ds_read_b128 v[140:143], v205 offset:8192
	v_mfma_f32_32x32x16_bf16 v[16:31], v[148:151], v[136:139], v[16:31]
	ds_read_b128 v[176:179], v211
	v_mfma_f32_32x32x16_bf16 v[0:15], v[128:131], v[136:139], v[0:15]
	ds_read_b128 v[182:185], v211 offset:8192
	s_waitcnt lgkmcnt(0)
	v_mfma_f32_32x32x16_bf16 v[144:159], v[132:135], v[160:163], 0
	ds_read_b128 v[186:189], v212
	v_exp_f32_e32 v220, v112
	v_exp_f32_e32 v221, v113
	v_exp_f32_e32 v222, v114
	v_exp_f32_e32 v223, v115
	v_mfma_f32_32x32x16_bf16 v[128:143], v[140:143], v[160:163], 0
	ds_read_b128 v[216:219], v212 offset:8192
	v_exp_f32_e32 v224, v116
	v_exp_f32_e32 v225, v117
	v_exp_f32_e32 v226, v118
	v_exp_f32_e32 v227, v119
	v_mfma_f32_32x32x16_bf16 v[144:159], v[176:179], v[164:167], v[144:159]
	ds_read_b128 v[116:119], v213
	v_exp_f32_e32 v228, v120
	v_exp_f32_e32 v229, v121
	v_exp_f32_e32 v230, v122
	v_exp_f32_e32 v231, v123
	v_cvt_pk_bf16_f32 v112, v220, v221
	v_cvt_pk_bf16_f32 v113, v222, v223
	v_cvt_pk_bf16_f32 v114, v224, v225
	v_cvt_pk_bf16_f32 v115, v226, v227
	v_pk_add_f32 v[122:123], v[226:227], v[222:223]
	v_pk_add_f32 v[120:121], v[224:225], v[220:221]
	v_mfma_f32_32x32x16_bf16 v[128:143], v[182:185], v[164:167], v[128:143]
	ds_read_b128 v[176:179], v213 offset:8192
	v_exp_f32_e32 v124, v124
	v_exp_f32_e32 v125, v125
	v_exp_f32_e32 v126, v126
	v_exp_f32_e32 v127, v127
	s_waitcnt lgkmcnt(0)
	v_mfma_f32_32x32x16_bf16 v[144:159], v[186:189], v[168:171], v[144:159]
	v_add_f32_e64 v122, v230, v122
	v_add_f32_e64 v123, v231, v123
	v_add_f32_e64 v120, v228, v120
	v_add_f32_e64 v121, v229, v121
	v_exp_f32_e32 v182, v96
	v_exp_f32_e32 v183, v97
	v_exp_f32_e32 v184, v98
	v_exp_f32_e32 v185, v99
	v_cvt_pk_bf16_f32 v96, v228, v229
	v_cvt_pk_bf16_f32 v97, v230, v231
	v_cvt_pk_bf16_f32 v98, v124, v125
	v_cvt_pk_bf16_f32 v99, v126, v127
	v_pk_add_f32 v[122:123], v[126:127], v[122:123]
	v_pk_add_f32 v[120:121], v[124:125], v[120:121]
	v_mfma_f32_32x32x16_bf16 v[128:143], v[216:219], v[168:171], v[128:143]
	v_exp_f32_e32 v124, v100
	v_exp_f32_e32 v125, v101
	v_exp_f32_e32 v126, v102
	v_exp_f32_e32 v127, v103
	v_mfma_f32_32x32x16_bf16 v[144:159], v[116:119], v[172:175], v[144:159]
	v_exp_f32_e32 v186, v104
	v_exp_f32_e32 v187, v105
	v_exp_f32_e32 v188, v106
	v_exp_f32_e32 v189, v107
	v_pk_add_f32 v[106:107], v[184:185], v[122:123]
	v_pk_add_f32 v[104:105], v[182:183], v[120:121]
	v_cvt_pk_bf16_f32 v100, v182, v183
	v_cvt_pk_bf16_f32 v101, v184, v185
	v_cvt_pk_bf16_f32 v102, v124, v125
	v_cvt_pk_bf16_f32 v103, v126, v127
	v_pk_add_f32 v[118:119], v[126:127], v[106:107]
	v_pk_add_f32 v[116:117], v[124:125], v[104:105]
	v_mfma_f32_32x32x16_bf16 v[128:143], v[176:179], v[172:175], v[128:143]
	v_exp_f32_e32 v120, v108
	v_exp_f32_e32 v121, v109
	v_exp_f32_e32 v122, v110
	v_exp_f32_e32 v123, v111
	v_pk_add_f32 v[110:111], v[188:189], v[118:119]
	v_pk_add_f32 v[108:109], v[186:187], v[116:117]
	v_cvt_pk_bf16_f32 v104, v186, v187
	v_cvt_pk_bf16_f32 v105, v188, v189
	v_cvt_pk_bf16_f32 v106, v120, v121
	v_cvt_pk_bf16_f32 v107, v122, v123
	v_pk_add_f32 v[178:179], v[122:123], v[110:111]
	v_pk_add_f32 v[176:177], v[120:121], v[108:109]
	s_waitcnt vmcnt(4) lgkmcnt(0)
	s_barrier
	s_add_u32 s70, s98, 0x18000
	s_addc_u32 s71, s99, 0
	s_add_i32 s68, 0, s57
	s_mov_b32 m0, s68
	s_nop 0
	global_load_lds_dwordx4 v198, s[70:71]
	s_add_i32 m0, s68, 0x400
	s_nop 0
	global_load_lds_dwordx4 v194, s[70:71]
	s_add_u32 s2, s100, 0x80
	s_addc_u32 s3, s101, 0
	s_add_i32 s49, s58, 0x8000
	s_add_i32 m0, s49, 0xc000
	s_nop 0
	global_load_lds_dwordx4 v196, s[2:3]
	s_add_i32 m0, s49, 0xc400
	s_nop 0
	global_load_lds_dwordx4 v192, s[2:3]
	s_add_i32 s2, s46, 0xffff4000
	ds_read_b128 v[108:111], v236 offset:32768
	ds_read_b128 v[116:119], v236 offset:36864
	ds_read_b128 v[120:123], v236 offset:40960
	ds_read_b128 v[124:127], v236 offset:45056
	s_waitcnt lgkmcnt(0)
	v_mfma_f32_32x32x16_bf16 v[80:95], v[108:111], v[112:115], v[80:95]
	ds_read_b128 v[108:111], v237 offset:32768
	v_mfma_f32_32x32x16_bf16 v[64:79], v[116:119], v[112:115], v[64:79]
	ds_read_b128 v[116:119], v237 offset:36864
	v_mfma_f32_32x32x16_bf16 v[16:31], v[120:123], v[112:115], v[16:31]
	ds_read_b128 v[120:123], v237 offset:40960
	v_mfma_f32_32x32x16_bf16 v[0:15], v[124:127], v[112:115], v[0:15]
	ds_read_b128 v[112:115], v237 offset:45056
	s_waitcnt lgkmcnt(0)
	v_mfma_f32_32x32x16_bf16 v[80:95], v[108:111], v[96:99], v[80:95]
	ds_read_b128 v[108:111], v238 offset:32768
	v_mfma_f32_32x32x16_bf16 v[64:79], v[116:119], v[96:99], v[64:79]
	ds_read_b128 v[116:119], v238 offset:36864
	v_mfma_f32_32x32x16_bf16 v[16:31], v[120:123], v[96:99], v[16:31]
	ds_read_b128 v[120:123], v238 offset:40960
	v_mfma_f32_32x32x16_bf16 v[0:15], v[112:115], v[96:99], v[0:15]
	ds_read_b128 v[96:99], v238 offset:45056
	s_waitcnt lgkmcnt(0)
	v_mfma_f32_32x32x16_bf16 v[80:95], v[108:111], v[100:103], v[80:95]
	ds_read_b128 v[108:111], v239 offset:32768
	v_mfma_f32_32x32x16_bf16 v[64:79], v[116:119], v[100:103], v[64:79]
	ds_read_b128 v[112:115], v239 offset:36864
	v_mfma_f32_32x32x16_bf16 v[16:31], v[120:123], v[100:103], v[16:31]
	ds_read_b128 v[116:119], v239 offset:40960
	v_mfma_f32_32x32x16_bf16 v[0:15], v[96:99], v[100:103], v[0:15]
	ds_read_b128 v[120:123], v239 offset:45056
	s_waitcnt lgkmcnt(0)
	v_mfma_f32_32x32x16_bf16 v[80:95], v[108:111], v[104:107], v[80:95]
	ds_read_b128 v[96:99], v205 offset:16384
	v_mfma_f32_32x32x16_bf16 v[64:79], v[112:115], v[104:107], v[64:79]
	ds_read_b128 v[100:103], v205 offset:24576
	v_mfma_f32_32x32x16_bf16 v[16:31], v[116:119], v[104:107], v[16:31]
	ds_read_b128 v[182:185], v211 offset:16384
	v_mfma_f32_32x32x16_bf16 v[0:15], v[120:123], v[104:107], v[0:15]
	ds_read_b128 v[186:189], v211 offset:24576
	s_waitcnt lgkmcnt(0)
	v_mfma_f32_32x32x16_bf16 v[112:127], v[96:99], v[160:163], 0
	ds_read_b128 v[216:219], v212 offset:16384
	v_exp_f32_e32 v224, v144
	v_exp_f32_e32 v225, v145
	v_exp_f32_e32 v226, v146
	v_exp_f32_e32 v227, v147
	ds_read_b128 v[220:223], v212 offset:24576
	v_mfma_f32_32x32x16_bf16 v[96:111], v[100:103], v[160:163], 0
	v_exp_f32_e32 v228, v148
	v_exp_f32_e32 v229, v149
	v_exp_f32_e32 v230, v150
	v_exp_f32_e32 v231, v151
	v_mfma_f32_32x32x16_bf16 v[112:127], v[182:185], v[164:167], v[112:127]
	ds_read_b128 v[148:151], v213 offset:16384
	v_exp_f32_e32 v232, v152
	v_exp_f32_e32 v233, v153
	v_exp_f32_e32 v234, v154
	v_exp_f32_e32 v235, v155
	v_cvt_pk_bf16_f32 v144, v224, v225
	v_cvt_pk_bf16_f32 v145, v226, v227
	v_cvt_pk_bf16_f32 v146, v228, v229
	v_cvt_pk_bf16_f32 v147, v230, v231
	v_pk_add_f32 v[154:155], v[230:231], v[226:227]
	v_pk_add_f32 v[152:153], v[228:229], v[224:225]
	v_mfma_f32_32x32x16_bf16 v[96:111], v[186:189], v[164:167], v[96:111]
	ds_read_b128 v[182:185], v213 offset:24576
	v_exp_f32_e32 v156, v156
	v_exp_f32_e32 v157, v157
	v_exp_f32_e32 v158, v158
	v_exp_f32_e32 v159, v159
	s_waitcnt lgkmcnt(0)
	v_mfma_f32_32x32x16_bf16 v[112:127], v[216:219], v[168:171], v[112:127]
	v_add_f32_e64 v154, v234, v154
	v_add_f32_e64 v155, v235, v155
	v_add_f32_e64 v152, v232, v152
	v_add_f32_e64 v153, v233, v153
	v_exp_f32_e32 v186, v128
	v_exp_f32_e32 v187, v129
	v_exp_f32_e32 v188, v130
	v_exp_f32_e32 v189, v131
	v_cvt_pk_bf16_f32 v128, v232, v233
	v_cvt_pk_bf16_f32 v129, v234, v235
	v_cvt_pk_bf16_f32 v130, v156, v157
	v_cvt_pk_bf16_f32 v131, v158, v159
	v_pk_add_f32 v[154:155], v[158:159], v[154:155]
	v_pk_add_f32 v[152:153], v[156:157], v[152:153]
	v_mfma_f32_32x32x16_bf16 v[96:111], v[220:223], v[168:171], v[96:111]
	v_exp_f32_e32 v156, v132
	v_exp_f32_e32 v157, v133
	v_exp_f32_e32 v158, v134
	v_exp_f32_e32 v159, v135
	v_mfma_f32_32x32x16_bf16 v[112:127], v[148:151], v[172:175], v[112:127]
	v_exp_f32_e32 v216, v136
	v_exp_f32_e32 v217, v137
	v_exp_f32_e32 v218, v138
	v_exp_f32_e32 v219, v139
	v_pk_add_f32 v[138:139], v[188:189], v[154:155]
	v_pk_add_f32 v[136:137], v[186:187], v[152:153]
	v_cvt_pk_bf16_f32 v132, v186, v187
	v_cvt_pk_bf16_f32 v133, v188, v189
	v_cvt_pk_bf16_f32 v134, v156, v157
	v_cvt_pk_bf16_f32 v135, v158, v159
	v_pk_add_f32 v[150:151], v[158:159], v[138:139]
	v_pk_add_f32 v[148:149], v[156:157], v[136:137]
	v_mfma_f32_32x32x16_bf16 v[96:111], v[182:185], v[172:175], v[96:111]
	v_exp_f32_e32 v152, v140
	v_exp_f32_e32 v153, v141
	v_exp_f32_e32 v154, v142
	v_exp_f32_e32 v155, v143
	v_pk_add_f32 v[142:143], v[218:219], v[150:151]
	v_pk_add_f32 v[140:141], v[216:217], v[148:149]
	v_cvt_pk_bf16_f32 v136, v216, v217
	v_cvt_pk_bf16_f32 v137, v218, v219
	v_cvt_pk_bf16_f32 v138, v152, v153
	v_cvt_pk_bf16_f32 v139, v154, v155
	v_pk_add_f32 v[142:143], v[154:155], v[142:143]
	v_pk_add_f32 v[140:141], v[152:153], v[140:141]
	s_waitcnt vmcnt(4) lgkmcnt(0)
	v_add_f32_e32 v148, v176, v177
	v_add_f32_e32 v149, v178, v179
	v_add_f32_e32 v148, v148, v149
	v_add_f32_e32 v140, v140, v141
	v_add_f32_e32 v141, v142, v143
	s_barrier
	v_add_f32_e32 v148, v180, v148
	v_add_f32_e32 v140, v140, v141
	v_add_f32_e32 v180, v148, v140
	s_add_i32 s47, s47, 2
	s_addk_i32 s41, 0x80
	s_add_i32 s46, s46, 0x8000
	s_add_u32 s98, s98, 0x30000
	s_addc_u32 s99, s99, 0
	s_add_u32 s100, s100, 0x100
	s_addc_u32 s101, s101, 0
	s_cmp_lt_u32 s47, 50
	s_cbranch_scc1 .Lst1_u6_loop
	s_cmp_lt_u32 s47, 60
	s_cbranch_scc1 .Lst1_single
